# row-scale (rstd) loads of EpiProj/EpiUp issued at the tile top, so the epilogue no longer starts by draining the next tile's DMA prefetch
# baseline (speedup 1.0000x reference)
; #define PG8_STAGE(bufoff, gbase, voff) do { _Pragma("unroll") for (int _i = 0; _i < 2; ++_i) \
;         __builtin_amdgcn_global_load_lds((const unsigned*)((const char*)(gbase) + (voff)[_i]), (LAS unsigned*)(lds + (bufoff) + ldsw + _i * 8192), 16, 0, 0); } while (0)
; #define PG8_LDA(dst, b, h) do { _Pragma("unroll") for (int m = 0; m < 4; ++m) _Pragma("unroll") for (int k = 0; k < 2; ++k) dst[m][k] = *(const LAS bf16x8*)(lds + PG8_SA(b, h) + aoff + m * 2048 + k * 1024); } while (0)
; #define PG8_LDB(dst, b, h) do { _Pragma("unroll") for (int n = 0; n < 2; ++n) _Pragma("unroll") for (int k = 0; k < 2; ++k) dst[n][k] = *(const LAS bf16x8*)(lds + PG8_SB(b, h) + boff + n * 2048 + k * 1024); } while (0)
; #define PG8_WAIT_L(n) asm volatile("s_waitcnt lgkmcnt(" #n ")" ::: "memory")
; #define PG8_BAR __builtin_amdgcn_s_barrier()
; #define PG8_SCHED __builtin_amdgcn_sched_barrier(0)
; template <class Epi>
; __device__ __forceinline__ void gemm_phase(LAS unsigned char* lds, const Gemm g, const StaticOrder& S, const Epi& E) {
;     ...
;         const bool has_next = S.next(ui + 1, nxt);
;         const char* nA = has_next ? (const char*)g.A + (size_t)nxt.pm * tstepA : cA; const char* nB = has_next ? (const char*)g.Bt + (size_t)nxt.pn * tstepB : cB;
;         for (int t = 0; t < nt; t += 2) {
;             const bool last = (t == nt - 2);
;             const char* a1 = cA + (size_t)(t + 1) * kstep;
;             const char* a2 = last ? nA : cA + (size_t)(t + 2) * kstep; const char* b2 = last ? nB : cB + (size_t)(t + 2) * kstep;
;             const char* a3 = a2 + kstep; const char* b3 = b2 + kstep;
;             PG8_LDB(B0, 0, 0); PG8_SCHED; PG8_LDA(At, 0, 0); PG8_STAGE(PG8_SA(1, 1), a1 + hstepA, voffA);
;             PG8_WAIT_L(8); PG8_BAR; PG8_WAIT_L(0); PG8_MMA(0, 0, At, B0); PG8_BAR; PG8_SCHED;
;     __device__ __forceinline__ void operator()(const f32x4 (&acc)[2][2][4][2], const pg8::Unit& u, int wr, int wc, int fr, int fq) const {
;         const int row0 = u.pm * 256 + wr * 64 + fr, col0 = u.pn * 256 + wc * 32 + 8 * fq;
; #pragma unroll
;         for (int ai = 0; ai < 2; ++ai)
; #pragma unroll
;             for (int m = 0; m < 4; ++m) { const int row = row0 + ai * 128 + m * 16; const float s = rstd[row]; bf16_t* rowp = O + (size_t)row * ldc + col0;
.LBB0_161:
	s_ashr_i32 s15, s14, 31
	v_cmp_lt_i64_e32 vcc, s[16:17], v[140:141]
	s_lshl_b64 s[16:17], s[14:15], 19
	s_add_u32 s16, s27, s16
	s_addc_u32 s17, s28, s17
	s_and_b64 s[20:21], vcc, exec
	s_cselect_b32 s15, s17, s31
	s_cselect_b32 s48, s16, s30
	s_ashr_i32 s13, s12, 31
	s_lshl_b64 s[20:21], s[12:13], 19
	s_add_u32 s20, s18, s20
	s_addc_u32 s21, s19, s21
	s_and_b64 s[36:37], vcc, exec
	s_cselect_b32 s13, s21, s35
	s_cselect_b32 s49, s20, s34
	s_add_u32 s30, s30, 0x40080
	s_addc_u32 s31, s31, 0
	s_add_u32 s50, s34, 0x100
	v_mov_b32_e32 v0, 0
	s_addc_u32 s51, s35, 0
	s_mov_b32 s52, -2
	v_mov_b32_e32 v1, v0
	v_mov_b32_e32 v2, v0
	v_mov_b32_e32 v3, v0
	v_mov_b32_e32 v4, v0
	v_mov_b32_e32 v5, v0
	v_mov_b32_e32 v6, v0
	v_mov_b32_e32 v7, v0
	v_mov_b32_e32 v16, v0
	v_mov_b32_e32 v17, v0
	v_mov_b32_e32 v18, v0
	v_mov_b32_e32 v19, v0
	v_mov_b32_e32 v20, v0
	v_mov_b32_e32 v21, v0
	v_mov_b32_e32 v22, v0
	v_mov_b32_e32 v23, v0
	v_mov_b32_e32 v32, v0
	v_mov_b32_e32 v33, v0
	v_mov_b32_e32 v34, v0
	v_mov_b32_e32 v35, v0
	v_mov_b32_e32 v36, v0
	v_mov_b32_e32 v37, v0
	v_mov_b32_e32 v38, v0
	v_mov_b32_e32 v39, v0
	v_mov_b32_e32 v48, v0
	v_mov_b32_e32 v49, v0
	v_mov_b32_e32 v50, v0
	v_mov_b32_e32 v51, v0
	v_mov_b32_e32 v52, v0
	v_mov_b32_e32 v53, v0
	v_mov_b32_e32 v54, v0
	v_mov_b32_e32 v55, v0
	v_mov_b32_e32 v8, v0
	v_mov_b32_e32 v9, v0
	v_mov_b32_e32 v10, v0
	v_mov_b32_e32 v11, v0
	v_mov_b32_e32 v12, v0
	v_mov_b32_e32 v13, v0
	v_mov_b32_e32 v14, v0
	v_mov_b32_e32 v15, v0
	v_mov_b32_e32 v24, v0
	v_mov_b32_e32 v25, v0
	v_mov_b32_e32 v26, v0
	v_mov_b32_e32 v27, v0
	v_mov_b32_e32 v28, v0
	v_mov_b32_e32 v29, v0
	v_mov_b32_e32 v30, v0
	v_mov_b32_e32 v31, v0
	v_mov_b32_e32 v40, v0
	v_mov_b32_e32 v41, v0
	v_mov_b32_e32 v42, v0
	v_mov_b32_e32 v43, v0
	v_mov_b32_e32 v44, v0
	v_mov_b32_e32 v45, v0
	v_mov_b32_e32 v46, v0
	v_mov_b32_e32 v47, v0
	v_mov_b32_e32 v56, v0
	v_mov_b32_e32 v57, v0
	v_mov_b32_e32 v58, v0
	v_mov_b32_e32 v59, v0
	v_mov_b32_e32 v60, v0
	v_mov_b32_e32 v61, v0
	v_mov_b32_e32 v62, v0
	v_mov_b32_e32 v63, v0
	v_mov_b32_e32 v64, v0
	v_mov_b32_e32 v65, v0
	v_mov_b32_e32 v66, v0
	v_mov_b32_e32 v67, v0
	v_mov_b32_e32 v68, v0
	v_mov_b32_e32 v69, v0
	v_mov_b32_e32 v70, v0
	v_mov_b32_e32 v71, v0
	v_mov_b32_e32 v80, v0
	v_mov_b32_e32 v81, v0
	v_mov_b32_e32 v82, v0
	v_mov_b32_e32 v83, v0
	v_mov_b32_e32 v84, v0
	v_mov_b32_e32 v85, v0
	v_mov_b32_e32 v86, v0
	v_mov_b32_e32 v87, v0
	v_mov_b32_e32 v96, v0
	v_mov_b32_e32 v97, v0
	v_mov_b32_e32 v98, v0
	v_mov_b32_e32 v99, v0
	v_mov_b32_e32 v100, v0
	v_mov_b32_e32 v101, v0
	v_mov_b32_e32 v102, v0
	v_mov_b32_e32 v103, v0
	v_mov_b32_e32 v112, v0
	v_mov_b32_e32 v113, v0
	v_mov_b32_e32 v114, v0
	v_mov_b32_e32 v115, v0
	v_mov_b32_e32 v116, v0
	v_mov_b32_e32 v117, v0
	v_mov_b32_e32 v118, v0
	v_mov_b32_e32 v119, v0
	v_mov_b32_e32 v72, v0
	v_mov_b32_e32 v73, v0
	v_mov_b32_e32 v74, v0
	v_mov_b32_e32 v75, v0
	v_mov_b32_e32 v76, v0
	v_mov_b32_e32 v77, v0
	v_mov_b32_e32 v78, v0
	v_mov_b32_e32 v79, v0
	v_mov_b32_e32 v88, v0
	v_mov_b32_e32 v89, v0
	v_mov_b32_e32 v90, v0
	v_mov_b32_e32 v91, v0
	v_mov_b32_e32 v92, v0
	v_mov_b32_e32 v93, v0
	v_mov_b32_e32 v94, v0
	v_mov_b32_e32 v95, v0
	v_mov_b32_e32 v104, v0
	v_mov_b32_e32 v105, v0
	v_mov_b32_e32 v106, v0
	v_mov_b32_e32 v107, v0
	v_mov_b32_e32 v108, v0
	v_mov_b32_e32 v109, v0
	v_mov_b32_e32 v110, v0
	v_mov_b32_e32 v111, v0
	v_mov_b32_e32 v120, v0
	v_mov_b32_e32 v121, v0
	v_mov_b32_e32 v122, v0
	v_mov_b32_e32 v123, v0
	v_mov_b32_e32 v124, v0
	v_mov_b32_e32 v125, v0
	v_mov_b32_e32 v126, v0
	v_mov_b32_e32 v127, v0
	v_lshl_add_u32 v244, s24, 8, v155
	v_ashrrev_i32_e32 v245, 31, v244
	v_lshl_add_u64 v[244:245], v[244:245], 2, s[8:9]
	global_load_dword v228, v[244:245], off
	global_load_dword v230, v[244:245], off offset:64
	global_load_dword v232, v[244:245], off offset:128
	global_load_dword v234, v[244:245], off offset:192
	global_load_dword v236, v[244:245], off offset:512
	global_load_dword v238, v[244:245], off offset:576
	global_load_dword v240, v[244:245], off offset:640
	global_load_dword v242, v[244:245], off offset:704
.LBB0_162:
	ds_read_b128 v[144:147], v158
	ds_read_b128 v[148:151], v158 offset:1024
	ds_read_b128 v[162:165], v158 offset:2048
	ds_read_b128 v[166:169], v158 offset:3072
	s_add_u32 s34, s30, 0xfffc0080
	s_addc_u32 s35, s31, -1
	s_cmp_eq_u32 s52, 12
	s_cselect_b32 s37, s15, s35
	s_cselect_b32 s36, s48, s34
	s_cselect_b32 s35, s13, s51
	s_cselect_b32 s34, s49, s50
	v_lshl_add_u64 v[174:175], s[30:31], 0, v[136:137]
	s_add_i32 m0, s25, 0xc000
	ds_read_b128 v[170:173], v159
	ds_read_b128 v[178:181], v159 offset:1024
	ds_read_b128 v[182:185], v159 offset:2048
	ds_read_b128 v[186:189], v159 offset:3072
	ds_read_b128 v[190:193], v159 offset:4096
	ds_read_b128 v[194:197], v159 offset:5120
	ds_read_b128 v[198:201], v159 offset:6144
	ds_read_b128 v[202:205], v159 offset:7168
	global_load_lds_dwordx4 v[174:175], off
	v_lshl_add_u64 v[174:175], s[30:31], 0, v[138:139]
	s_add_i32 m0, s25, 0xe000
	s_nop 0
	global_load_lds_dwordx4 v[174:175], off
	s_waitcnt lgkmcnt(8)
	s_barrier
; #define PG8_STAGE(bufoff, gbase, voff) do { _Pragma("unroll") for (int _i = 0; _i < 2; ++_i) \
;         __builtin_amdgcn_global_load_lds((const unsigned*)((const char*)(gbase) + (voff)[_i]), (LAS unsigned*)(lds + (bufoff) + ldsw + _i * 8192), 16, 0, 0); } while (0)
; #define PG8_LDA(dst, b, h) do { _Pragma("unroll") for (int m = 0; m < 4; ++m) _Pragma("unroll") for (int k = 0; k < 2; ++k) dst[m][k] = *(const LAS bf16x8*)(lds + PG8_SA(b, h) + aoff + m * 2048 + k * 1024); } while (0)
; #define PG8_LDB(dst, b, h) do { _Pragma("unroll") for (int n = 0; n < 2; ++n) _Pragma("unroll") for (int k = 0; k < 2; ++k) dst[n][k] = *(const LAS bf16x8*)(lds + PG8_SB(b, h) + boff + n * 2048 + k * 1024); } while (0)
; #define PG8_MMA(ai, bj, At, Bt) do { __builtin_amdgcn_s_setprio(1); _Pragma("unroll") for (int m = 0; m < 4; ++m) _Pragma("unroll") for (int n = 0; n < 2; ++n) _Pragma("unroll") for (int k = 0; k < 2; ++k) \
;         acc[ai][bj][m][n] = __builtin_amdgcn_mfma_f32_16x16x32_bf16(Bt[n][k], At[m][k], acc[ai][bj][m][n], 0, 0, 0); __builtin_amdgcn_s_setprio(0); } while (0)
; #define PG8_WAIT_V(n) asm volatile("s_waitcnt vmcnt(" #n ")" ::: "memory")
; #define PG8_WAIT_L(n) asm volatile("s_waitcnt lgkmcnt(" #n ")" ::: "memory")
; #define PG8_BAR __builtin_amdgcn_s_barrier()
; #define PG8_SCHED __builtin_amdgcn_sched_barrier(0)
; template <class Epi>
; __device__ __forceinline__ void gemm_phase(LAS unsigned char* lds, const Gemm g, const StaticOrder& S, const Epi& E) {
;     ...
;             PG8_LDB(B0, 0, 0); PG8_SCHED; PG8_LDA(At, 0, 0); PG8_STAGE(PG8_SA(1, 1), a1 + hstepA, voffA);
;             PG8_WAIT_L(8); PG8_BAR; PG8_WAIT_L(0); PG8_MMA(0, 0, At, B0); PG8_BAR; PG8_SCHED;
;             PG8_LDB(B1, 0, 1); PG8_STAGE(PG8_SB(0, 0), b2, voffB);
;             PG8_BAR; PG8_WAIT_L(0); PG8_MMA(0, 1, At, B1); PG8_BAR;
;             PG8_LDA(At, 0, 1); PG8_STAGE(PG8_SA(0, 0), a2, voffA);
;             PG8_BAR; PG8_WAIT_L(0); PG8_MMA(1, 0, At, B0); PG8_BAR; PG8_SCHED;
;             PG8_STAGE(PG8_SB(0, 1), b2 + hstepB, voffB);
;             PG8_WAIT_V(6); PG8_BAR; PG8_MMA(1, 1, At, B1); PG8_BAR;
	s_waitcnt lgkmcnt(0)
	s_setprio 1
	s_waitcnt lgkmcnt(0)
	v_mfma_f32_16x16x32_bf16 v[124:127], v[144:147], v[170:173], v[124:127]
	v_mfma_f32_16x16x32_bf16 v[120:123], v[162:165], v[170:173], v[120:123]
	v_mfma_f32_16x16x32_bf16 v[108:111], v[144:147], v[182:185], v[108:111]
	v_mfma_f32_16x16x32_bf16 v[104:107], v[162:165], v[182:185], v[104:107]
	v_mfma_f32_16x16x32_bf16 v[92:95], v[144:147], v[190:193], v[92:95]
	v_mfma_f32_16x16x32_bf16 v[88:91], v[162:165], v[190:193], v[88:91]
	v_mfma_f32_16x16x32_bf16 v[76:79], v[144:147], v[198:201], v[76:79]
	v_mfma_f32_16x16x32_bf16 v[72:75], v[162:165], v[198:201], v[72:75]
	v_mfma_f32_16x16x32_bf16 v[124:127], v[148:151], v[178:181], v[124:127]
	v_mfma_f32_16x16x32_bf16 v[120:123], v[166:169], v[178:181], v[120:123]
	v_mfma_f32_16x16x32_bf16 v[108:111], v[148:151], v[186:189], v[108:111]
	v_mfma_f32_16x16x32_bf16 v[104:107], v[166:169], v[186:189], v[104:107]
	v_mfma_f32_16x16x32_bf16 v[92:95], v[148:151], v[194:197], v[92:95]
	v_mfma_f32_16x16x32_bf16 v[88:91], v[166:169], v[194:197], v[88:91]
	v_mfma_f32_16x16x32_bf16 v[76:79], v[148:151], v[202:205], v[76:79]
	v_mfma_f32_16x16x32_bf16 v[72:75], v[166:169], v[202:205], v[72:75]
	s_setprio 0
	s_barrier
	s_add_i32 s53, s45, s29
	v_lshl_add_u64 v[174:175], s[34:35], 0, v[130:131]
	s_mov_b32 m0, s53
	ds_read_b128 v[206:209], v160
	ds_read_b128 v[210:213], v160 offset:1024
	ds_read_b128 v[214:217], v160 offset:2048
	ds_read_b128 v[218:221], v160 offset:3072
	global_load_lds_dwordx4 v[174:175], off
	v_lshl_add_u64 v[222:223], s[34:35], 0, v[134:135]
	s_add_i32 m0, s53, 0x2000
	s_nop 0
	global_load_lds_dwordx4 v[222:223], off
	s_barrier
	s_waitcnt lgkmcnt(0)
	s_setprio 1
	s_waitcnt lgkmcnt(0)
	v_mfma_f32_16x16x32_bf16 v[116:119], v[206:209], v[170:173], v[116:119]
	v_mfma_f32_16x16x32_bf16 v[112:115], v[214:217], v[170:173], v[112:115]
	v_mfma_f32_16x16x32_bf16 v[100:103], v[206:209], v[182:185], v[100:103]
	v_mfma_f32_16x16x32_bf16 v[96:99], v[214:217], v[182:185], v[96:99]
	v_mfma_f32_16x16x32_bf16 v[84:87], v[206:209], v[190:193], v[84:87]
	v_mfma_f32_16x16x32_bf16 v[80:83], v[214:217], v[190:193], v[80:83]
	v_mfma_f32_16x16x32_bf16 v[68:71], v[206:209], v[198:201], v[68:71]
	v_mfma_f32_16x16x32_bf16 v[64:67], v[214:217], v[198:201], v[64:67]
	v_mfma_f32_16x16x32_bf16 v[116:119], v[210:213], v[178:181], v[116:119]
	v_mfma_f32_16x16x32_bf16 v[112:115], v[218:221], v[178:181], v[112:115]
	v_mfma_f32_16x16x32_bf16 v[100:103], v[210:213], v[186:189], v[100:103]
	v_mfma_f32_16x16x32_bf16 v[96:99], v[218:221], v[186:189], v[96:99]
	v_mfma_f32_16x16x32_bf16 v[84:87], v[210:213], v[194:197], v[84:87]
	v_mfma_f32_16x16x32_bf16 v[80:83], v[218:221], v[194:197], v[80:83]
	v_mfma_f32_16x16x32_bf16 v[68:71], v[210:213], v[202:205], v[68:71]
	v_mfma_f32_16x16x32_bf16 v[64:67], v[218:221], v[202:205], v[64:67]
	s_setprio 0
	s_mov_b32 m0, s25
	v_lshl_add_u64 v[224:225], s[36:37], 0, v[128:129]
	s_barrier
	ds_read_b128 v[170:173], v159 offset:16384
	ds_read_b128 v[178:181], v159 offset:17408
	ds_read_b128 v[182:185], v159 offset:18432
	ds_read_b128 v[186:189], v159 offset:19456
	ds_read_b128 v[190:193], v159 offset:20480
	ds_read_b128 v[194:197], v159 offset:21504
	ds_read_b128 v[198:201], v159 offset:22528
	ds_read_b128 v[202:205], v159 offset:23552
	global_load_lds_dwordx4 v[224:225], off
	v_lshl_add_u64 v[226:227], s[36:37], 0, v[132:133]
	s_mov_b32 m0, s33
	s_nop 0
	global_load_lds_dwordx4 v[226:227], off
	s_barrier
	s_waitcnt lgkmcnt(0)
	s_setprio 1
	s_waitcnt lgkmcnt(0)
	v_mfma_f32_16x16x32_bf16 v[60:63], v[144:147], v[170:173], v[60:63]
	v_mfma_f32_16x16x32_bf16 v[56:59], v[162:165], v[170:173], v[56:59]
	v_mfma_f32_16x16x32_bf16 v[44:47], v[144:147], v[182:185], v[44:47]
	v_mfma_f32_16x16x32_bf16 v[40:43], v[162:165], v[182:185], v[40:43]
	v_mfma_f32_16x16x32_bf16 v[28:31], v[144:147], v[190:193], v[28:31]
	v_mfma_f32_16x16x32_bf16 v[24:27], v[162:165], v[190:193], v[24:27]
	v_mfma_f32_16x16x32_bf16 v[12:15], v[144:147], v[198:201], v[12:15]
	v_mfma_f32_16x16x32_bf16 v[8:11], v[162:165], v[198:201], v[8:11]
	v_mfma_f32_16x16x32_bf16 v[60:63], v[148:151], v[178:181], v[60:63]
	v_mfma_f32_16x16x32_bf16 v[56:59], v[166:169], v[178:181], v[56:59]
	v_mfma_f32_16x16x32_bf16 v[44:47], v[148:151], v[186:189], v[44:47]
	v_mfma_f32_16x16x32_bf16 v[40:43], v[166:169], v[186:189], v[40:43]
	v_mfma_f32_16x16x32_bf16 v[28:31], v[148:151], v[194:197], v[28:31]
	v_mfma_f32_16x16x32_bf16 v[24:27], v[166:169], v[194:197], v[24:27]
	v_mfma_f32_16x16x32_bf16 v[12:15], v[148:151], v[202:205], v[12:15]
	v_mfma_f32_16x16x32_bf16 v[8:11], v[166:169], v[202:205], v[8:11]
	s_setprio 0
	s_barrier
	s_add_u32 s54, s34, 0x40000
	s_addc_u32 s55, s35, 0
	s_add_i32 s53, s46, s29
	v_lshl_add_u64 v[144:145], s[54:55], 0, v[130:131]
	s_mov_b32 m0, s53
	s_nop 0
	global_load_lds_dwordx4 v[144:145], off
	v_lshl_add_u64 v[144:145], s[54:55], 0, v[134:135]
	s_add_i32 m0, s53, 0x2000
	s_nop 0
	global_load_lds_dwordx4 v[144:145], off
	s_waitcnt vmcnt(6)
	s_barrier
	s_setprio 1
	v_mfma_f32_16x16x32_bf16 v[52:55], v[206:209], v[170:173], v[52:55]
	v_mfma_f32_16x16x32_bf16 v[48:51], v[214:217], v[170:173], v[48:51]
	v_mfma_f32_16x16x32_bf16 v[36:39], v[206:209], v[182:185], v[36:39]
	v_mfma_f32_16x16x32_bf16 v[32:35], v[214:217], v[182:185], v[32:35]
	v_mfma_f32_16x16x32_bf16 v[20:23], v[206:209], v[190:193], v[20:23]
	v_mfma_f32_16x16x32_bf16 v[16:19], v[214:217], v[190:193], v[16:19]
	v_mfma_f32_16x16x32_bf16 v[4:7], v[206:209], v[198:201], v[4:7]
	v_mfma_f32_16x16x32_bf16 v[0:3], v[214:217], v[198:201], v[0:3]
	v_mfma_f32_16x16x32_bf16 v[52:55], v[210:213], v[178:181], v[52:55]
	v_mfma_f32_16x16x32_bf16 v[48:51], v[218:221], v[178:181], v[48:51]
	v_mfma_f32_16x16x32_bf16 v[36:39], v[210:213], v[186:189], v[36:39]
	v_mfma_f32_16x16x32_bf16 v[32:35], v[218:221], v[186:189], v[32:35]
	v_mfma_f32_16x16x32_bf16 v[20:23], v[210:213], v[194:197], v[20:23]
	v_mfma_f32_16x16x32_bf16 v[16:19], v[218:221], v[194:197], v[16:19]
	v_mfma_f32_16x16x32_bf16 v[4:7], v[210:213], v[202:205], v[4:7]
	v_mfma_f32_16x16x32_bf16 v[0:3], v[218:221], v[202:205], v[0:3]
	s_setprio 0
	s_add_i32 s53, 0, 0x18000
	v_add_u32_e32 v161, s53, v156
	s_barrier
; #define PG8_STAGE(bufoff, gbase, voff) do { _Pragma("unroll") for (int _i = 0; _i < 2; ++_i) \
;         __builtin_amdgcn_global_load_lds((const unsigned*)((const char*)(gbase) + (voff)[_i]), (LAS unsigned*)(lds + (bufoff) + ldsw + _i * 8192), 16, 0, 0); } while (0)
; #define PG8_LDA(dst, b, h) do { _Pragma("unroll") for (int m = 0; m < 4; ++m) _Pragma("unroll") for (int k = 0; k < 2; ++k) dst[m][k] = *(const LAS bf16x8*)(lds + PG8_SA(b, h) + aoff + m * 2048 + k * 1024); } while (0)
; #define PG8_LDB(dst, b, h) do { _Pragma("unroll") for (int n = 0; n < 2; ++n) _Pragma("unroll") for (int k = 0; k < 2; ++k) dst[n][k] = *(const LAS bf16x8*)(lds + PG8_SB(b, h) + boff + n * 2048 + k * 1024); } while (0)
; #define PG8_MMA(ai, bj, At, Bt) do { __builtin_amdgcn_s_setprio(1); _Pragma("unroll") for (int m = 0; m < 4; ++m) _Pragma("unroll") for (int n = 0; n < 2; ++n) _Pragma("unroll") for (int k = 0; k < 2; ++k) \
;         acc[ai][bj][m][n] = __builtin_amdgcn_mfma_f32_16x16x32_bf16(Bt[n][k], At[m][k], acc[ai][bj][m][n], 0, 0, 0); __builtin_amdgcn_s_setprio(0); } while (0)
; #define PG8_WAIT_L(n) asm volatile("s_waitcnt lgkmcnt(" #n ")" ::: "memory")
; #define PG8_BAR __builtin_amdgcn_s_barrier()
; #define PG8_SCHED __builtin_amdgcn_sched_barrier(0)
; template <class Epi>
; __device__ __forceinline__ void gemm_phase(LAS unsigned char* lds, const Gemm g, const StaticOrder& S, const Epi& E) {
;     ...
;             PG8_LDB(B0, 1, 0); PG8_SCHED; PG8_LDA(At, 1, 0); PG8_STAGE(PG8_SA(0, 1), a2 + hstepA, voffA);
;             PG8_WAIT_L(8); PG8_BAR; PG8_WAIT_L(0); PG8_MMA(0, 0, At, B0); PG8_BAR; PG8_SCHED;
;             PG8_LDB(B1, 1, 1); PG8_STAGE(PG8_SB(1, 0), b3, voffB);
;             PG8_BAR; PG8_WAIT_L(0); PG8_MMA(0, 1, At, B1); PG8_BAR;
;             PG8_LDA(At, 1, 1); PG8_STAGE(PG8_SA(1, 0), a3, voffA);
;             PG8_BAR; PG8_WAIT_L(0); PG8_MMA(1, 0, At, B0); PG8_BAR; PG8_SCHED;
	ds_read_b128 v[144:147], v161
	ds_read_b128 v[148:151], v161 offset:1024
	ds_read_b128 v[162:165], v161 offset:2048
	ds_read_b128 v[166:169], v161 offset:3072
	s_add_u32 s36, s36, 0x40000
	s_addc_u32 s37, s37, 0
	s_mov_b32 m0, s38
	v_lshl_add_u64 v[206:207], s[36:37], 0, v[128:129]
	ds_read_b128 v[170:173], v159 offset:32768
	ds_read_b128 v[178:181], v159 offset:33792
	ds_read_b128 v[182:185], v159 offset:34816
	ds_read_b128 v[186:189], v159 offset:35840
	ds_read_b128 v[190:193], v159 offset:36864
	ds_read_b128 v[194:197], v159 offset:37888
	ds_read_b128 v[198:201], v159 offset:38912
	ds_read_b128 v[202:205], v159 offset:39936
	global_load_lds_dwordx4 v[206:207], off
	v_lshl_add_u64 v[206:207], s[36:37], 0, v[132:133]
	s_mov_b32 m0, s39
	s_nop 0
	global_load_lds_dwordx4 v[206:207], off
	s_waitcnt lgkmcnt(8)
	s_barrier
	s_waitcnt lgkmcnt(0)
	s_setprio 1
	s_waitcnt lgkmcnt(0)
	v_mfma_f32_16x16x32_bf16 v[124:127], v[144:147], v[170:173], v[124:127]
	v_mfma_f32_16x16x32_bf16 v[120:123], v[162:165], v[170:173], v[120:123]
	v_mfma_f32_16x16x32_bf16 v[108:111], v[144:147], v[182:185], v[108:111]
	v_mfma_f32_16x16x32_bf16 v[104:107], v[162:165], v[182:185], v[104:107]
	v_mfma_f32_16x16x32_bf16 v[92:95], v[144:147], v[190:193], v[92:95]
	v_mfma_f32_16x16x32_bf16 v[88:91], v[162:165], v[190:193], v[88:91]
	v_mfma_f32_16x16x32_bf16 v[76:79], v[144:147], v[198:201], v[76:79]
	v_mfma_f32_16x16x32_bf16 v[72:75], v[162:165], v[198:201], v[72:75]
	v_mfma_f32_16x16x32_bf16 v[124:127], v[148:151], v[178:181], v[124:127]
	v_mfma_f32_16x16x32_bf16 v[120:123], v[166:169], v[178:181], v[120:123]
	v_mfma_f32_16x16x32_bf16 v[108:111], v[148:151], v[186:189], v[108:111]
	v_mfma_f32_16x16x32_bf16 v[104:107], v[166:169], v[186:189], v[104:107]
	v_mfma_f32_16x16x32_bf16 v[92:95], v[148:151], v[194:197], v[92:95]
	v_mfma_f32_16x16x32_bf16 v[88:91], v[166:169], v[194:197], v[88:91]
	v_mfma_f32_16x16x32_bf16 v[76:79], v[148:151], v[202:205], v[76:79]
	v_mfma_f32_16x16x32_bf16 v[72:75], v[166:169], v[202:205], v[72:75]
	s_setprio 0
	s_barrier
	s_add_i32 s36, 0, 0x1c000
	s_add_i32 s37, s53, s29
	v_add_u32_e32 v161, s36, v156
	v_lshl_add_u64 v[174:175], v[174:175], 0, s[10:11]
	s_mov_b32 m0, s37
	ds_read_b128 v[206:209], v161
	ds_read_b128 v[210:213], v161 offset:1024
	ds_read_b128 v[214:217], v161 offset:2048
	ds_read_b128 v[218:221], v161 offset:3072
	global_load_lds_dwordx4 v[174:175], off
	v_lshl_add_u64 v[174:175], v[222:223], 0, s[10:11]
	s_add_i32 m0, s37, 0x2000
	s_nop 0
	global_load_lds_dwordx4 v[174:175], off
	s_barrier
	s_waitcnt lgkmcnt(0)
	s_setprio 1
	s_waitcnt lgkmcnt(0)
	v_mfma_f32_16x16x32_bf16 v[116:119], v[206:209], v[170:173], v[116:119]
	v_mfma_f32_16x16x32_bf16 v[112:115], v[214:217], v[170:173], v[112:115]
	v_mfma_f32_16x16x32_bf16 v[100:103], v[206:209], v[182:185], v[100:103]
	v_mfma_f32_16x16x32_bf16 v[96:99], v[214:217], v[182:185], v[96:99]
	v_mfma_f32_16x16x32_bf16 v[84:87], v[206:209], v[190:193], v[84:87]
	v_mfma_f32_16x16x32_bf16 v[80:83], v[214:217], v[190:193], v[80:83]
	v_mfma_f32_16x16x32_bf16 v[68:71], v[206:209], v[198:201], v[68:71]
	v_mfma_f32_16x16x32_bf16 v[64:67], v[214:217], v[198:201], v[64:67]
	v_mfma_f32_16x16x32_bf16 v[116:119], v[210:213], v[178:181], v[116:119]
	v_mfma_f32_16x16x32_bf16 v[112:115], v[218:221], v[178:181], v[112:115]
	v_mfma_f32_16x16x32_bf16 v[100:103], v[210:213], v[186:189], v[100:103]
	v_mfma_f32_16x16x32_bf16 v[96:99], v[218:221], v[186:189], v[96:99]
	v_mfma_f32_16x16x32_bf16 v[84:87], v[210:213], v[194:197], v[84:87]
	v_mfma_f32_16x16x32_bf16 v[80:83], v[218:221], v[194:197], v[80:83]
	v_mfma_f32_16x16x32_bf16 v[68:71], v[210:213], v[202:205], v[68:71]
	v_mfma_f32_16x16x32_bf16 v[64:67], v[218:221], v[202:205], v[64:67]
	s_setprio 0
	s_mov_b32 m0, s41
	v_lshl_add_u64 v[174:175], v[224:225], 0, s[10:11]
	s_barrier
	ds_read_b128 v[170:173], v159 offset:49152
	ds_read_b128 v[178:181], v159 offset:50176
	ds_read_b128 v[182:185], v159 offset:51200
	ds_read_b128 v[186:189], v159 offset:52224
	ds_read_b128 v[190:193], v159 offset:53248
	ds_read_b128 v[194:197], v159 offset:54272
	ds_read_b128 v[198:201], v159 offset:55296
	ds_read_b128 v[202:205], v159 offset:56320
	global_load_lds_dwordx4 v[174:175], off
	v_lshl_add_u64 v[174:175], v[226:227], 0, s[10:11]
	s_mov_b32 m0, s42
	s_nop 0
	global_load_lds_dwordx4 v[174:175], off
	s_barrier
	s_waitcnt lgkmcnt(0)
	s_setprio 1
	s_waitcnt lgkmcnt(0)
	v_mfma_f32_16x16x32_bf16 v[60:63], v[144:147], v[170:173], v[60:63]
	v_mfma_f32_16x16x32_bf16 v[56:59], v[162:165], v[170:173], v[56:59]
	v_mfma_f32_16x16x32_bf16 v[44:47], v[144:147], v[182:185], v[44:47]
	v_mfma_f32_16x16x32_bf16 v[40:43], v[162:165], v[182:185], v[40:43]
	v_mfma_f32_16x16x32_bf16 v[28:31], v[144:147], v[190:193], v[28:31]
	v_mfma_f32_16x16x32_bf16 v[24:27], v[162:165], v[190:193], v[24:27]
	v_mfma_f32_16x16x32_bf16 v[12:15], v[144:147], v[198:201], v[12:15]
	v_mfma_f32_16x16x32_bf16 v[8:11], v[162:165], v[198:201], v[8:11]
	v_mfma_f32_16x16x32_bf16 v[60:63], v[148:151], v[178:181], v[60:63]
	v_mfma_f32_16x16x32_bf16 v[56:59], v[166:169], v[178:181], v[56:59]
	v_mfma_f32_16x16x32_bf16 v[44:47], v[148:151], v[186:189], v[44:47]
	v_mfma_f32_16x16x32_bf16 v[40:43], v[166:169], v[186:189], v[40:43]
	v_mfma_f32_16x16x32_bf16 v[28:31], v[148:151], v[194:197], v[28:31]
	v_mfma_f32_16x16x32_bf16 v[24:27], v[166:169], v[194:197], v[24:27]
	v_mfma_f32_16x16x32_bf16 v[12:15], v[148:151], v[202:205], v[12:15]
	v_mfma_f32_16x16x32_bf16 v[8:11], v[166:169], v[202:205], v[8:11]
	s_setprio 0
	s_barrier
; __device__ __forceinline__ unsigned pk2(float lo, float hi) { f32x2 v; v.x = lo; v.y = hi; return __builtin_bit_cast(unsigned, __builtin_convertvector(v, hwbf2)); }
; #define PG8_STAGE(bufoff, gbase, voff) do { _Pragma("unroll") for (int _i = 0; _i < 2; ++_i) \
;         __builtin_amdgcn_global_load_lds((const unsigned*)((const char*)(gbase) + (voff)[_i]), (LAS unsigned*)(lds + (bufoff) + ldsw + _i * 8192), 16, 0, 0); } while (0)
; #define PG8_MMA(ai, bj, At, Bt) do { __builtin_amdgcn_s_setprio(1); _Pragma("unroll") for (int m = 0; m < 4; ++m) _Pragma("unroll") for (int n = 0; n < 2; ++n) _Pragma("unroll") for (int k = 0; k < 2; ++k) \
;         acc[ai][bj][m][n] = __builtin_amdgcn_mfma_f32_16x16x32_bf16(Bt[n][k], At[m][k], acc[ai][bj][m][n], 0, 0, 0); __builtin_amdgcn_s_setprio(0); } while (0)
; #define PG8_WAIT_V(n) asm volatile("s_waitcnt vmcnt(" #n ")" ::: "memory")
; #define PG8_BAR __builtin_amdgcn_s_barrier()
; template <class Epi>
; __device__ __forceinline__ void gemm_phase(LAS unsigned char* lds, const Gemm g, const StaticOrder& S, const Epi& E) {
;     ...
;             PG8_STAGE(PG8_SB(1, 1), b3 + hstepB, voffB);
;             PG8_WAIT_V(6); PG8_BAR; PG8_MMA(1, 1, At, B1); PG8_BAR;
;         }
;     __device__ __forceinline__ void operator()(const f32x4 (&acc)[2][2][4][2], const pg8::Unit& u, int wr, int wc, int fr, int fq) const {
;         const int row0 = u.pm * 256 + wr * 64 + fr, col0 = u.pn * 256 + wc * 32 + 8 * fq;
; #pragma unroll
;         for (int ai = 0; ai < 2; ++ai)
; #pragma unroll
;             for (int m = 0; m < 4; ++m) { const int row = row0 + ai * 128 + m * 16; const float s = rstd[row]; bf16_t* rowp = O + (size_t)row * ldc + col0;
; #pragma unroll
;                 for (int bj = 0; bj < 2; ++bj) { const f32x4 v0 = acc[ai][bj][m][0] * s, v1 = acc[ai][bj][m][1] * s;
;                     u32x4 w; w.x = pk2(v0[0], v0[1]); w.y = pk2(v0[2], v0[3]); w.z = pk2(v1[0], v1[1]); w.w = pk2(v1[2], v1[3]);
;                     *(u32x4*)(rowp + bj * 128) = w; } }
	s_add_u32 s34, s34, 0x40080
	s_addc_u32 s35, s35, 0
	s_add_i32 s36, s36, s29
	v_lshl_add_u64 v[144:145], s[34:35], 0, v[130:131]
	s_mov_b32 m0, s36
	s_nop 0
	global_load_lds_dwordx4 v[144:145], off
	v_lshl_add_u64 v[144:145], s[34:35], 0, v[134:135]
	s_add_i32 m0, s36, 0x2000
	s_nop 0
	global_load_lds_dwordx4 v[144:145], off
	s_waitcnt vmcnt(6)
	s_barrier
	s_setprio 1
	v_mfma_f32_16x16x32_bf16 v[52:55], v[206:209], v[170:173], v[52:55]
	v_mfma_f32_16x16x32_bf16 v[48:51], v[214:217], v[170:173], v[48:51]
	v_mfma_f32_16x16x32_bf16 v[36:39], v[206:209], v[182:185], v[36:39]
	v_mfma_f32_16x16x32_bf16 v[32:35], v[214:217], v[182:185], v[32:35]
	v_mfma_f32_16x16x32_bf16 v[20:23], v[206:209], v[190:193], v[20:23]
	v_mfma_f32_16x16x32_bf16 v[16:19], v[214:217], v[190:193], v[16:19]
	v_mfma_f32_16x16x32_bf16 v[4:7], v[206:209], v[198:201], v[4:7]
	v_mfma_f32_16x16x32_bf16 v[0:3], v[214:217], v[198:201], v[0:3]
	v_mfma_f32_16x16x32_bf16 v[52:55], v[210:213], v[178:181], v[52:55]
	v_mfma_f32_16x16x32_bf16 v[48:51], v[218:221], v[178:181], v[48:51]
	v_mfma_f32_16x16x32_bf16 v[36:39], v[210:213], v[186:189], v[36:39]
	v_mfma_f32_16x16x32_bf16 v[32:35], v[218:221], v[186:189], v[32:35]
	v_mfma_f32_16x16x32_bf16 v[20:23], v[210:213], v[194:197], v[20:23]
	v_mfma_f32_16x16x32_bf16 v[16:19], v[218:221], v[194:197], v[16:19]
	v_mfma_f32_16x16x32_bf16 v[4:7], v[210:213], v[202:205], v[4:7]
	v_mfma_f32_16x16x32_bf16 v[0:3], v[218:221], v[202:205], v[0:3]
	s_setprio 0
	s_add_i32 s52, s52, 2
	s_add_u32 s30, s30, 0x100
	s_addc_u32 s31, s31, 0
	s_add_u32 s50, s50, 0x100
	s_addc_u32 s51, s51, 0
	s_cmp_gt_u32 s52, 13
	s_barrier
	s_cbranch_scc0 .LBB0_162
	v_lshl_add_u32 v148, s24, 8, v155
	v_ashrrev_i32_e32 v149, 31, v148
	v_lshl_add_u64 v[144:145], v[148:149], 2, s[8:9]
	v_lshl_or_b32 v146, s47, 8, v157
	v_ashrrev_i32_e32 v147, 31, v146
	v_lshlrev_b64 v[166:167], 12, v[148:149]
	v_or_b32_e32 v164, 16, v148
	v_lshlrev_b64 v[150:151], 1, v[146:147]
	v_lshl_add_u64 v[146:147], s[6:7], 0, v[166:167]
	v_ashrrev_i32_e32 v165, 31, v164
	v_lshl_add_u64 v[146:147], v[146:147], 0, v[150:151]
	v_lshl_add_u64 v[166:167], v[164:165], 2, s[8:9]
	s_mov_b32 s13, 0x80000
	s_mov_b64 s[30:31], 0x80000
	s_mov_b64 s[36:37], 0xb0000
	s_mov_b32 s47, s12
	s_mov_b32 s24, s14
	s_mov_b64 s[34:35], s[20:21]
	v_pk_mul_f32 v[126:127], v[126:127], v[228:229] op_sel_hi:[1,0]
	v_pk_mul_f32 v[124:125], v[124:125], v[228:229] op_sel_hi:[1,0]
	v_pk_mul_f32 v[122:123], v[122:123], v[228:229] op_sel_hi:[1,0]
	v_pk_mul_f32 v[120:121], v[120:121], v[228:229] op_sel_hi:[1,0]
	v_pk_mul_f32 v[118:119], v[118:119], v[228:229] op_sel_hi:[1,0]
	v_pk_mul_f32 v[116:117], v[116:117], v[228:229] op_sel_hi:[1,0]
	v_pk_mul_f32 v[168:169], v[114:115], v[228:229] op_sel_hi:[1,0]
	v_pk_mul_f32 v[162:163], v[112:113], v[228:229] op_sel_hi:[1,0]
	v_cvt_pk_bf16_f32 v112, v124, v125
	v_cvt_pk_bf16_f32 v113, v126, v127
	v_cvt_pk_bf16_f32 v114, v120, v121
	v_cvt_pk_bf16_f32 v115, v122, v123
	v_cvt_pk_bf16_f32 v116, v116, v117
	v_cvt_pk_bf16_f32 v117, v118, v119
	v_cvt_pk_bf16_f32 v118, v162, v163
	v_cvt_pk_bf16_f32 v119, v168, v169
	global_store_dwordx4 v[146:147], v[112:115], off
	global_store_dwordx4 v[146:147], v[116:119], off offset:256
	v_or_b32_e32 v114, 32, v148
	v_lshlrev_b64 v[116:117], 12, v[164:165]
	v_lshl_add_u64 v[116:117], s[6:7], 0, v[116:117]
	v_ashrrev_i32_e32 v115, 31, v114
	v_lshl_add_u64 v[116:117], v[116:117], 0, v[150:151]
	v_lshl_add_u64 v[118:119], v[114:115], 2, s[8:9]
	v_pk_mul_f32 v[110:111], v[110:111], v[230:231] op_sel_hi:[1,0]
	v_pk_mul_f32 v[108:109], v[108:109], v[230:231] op_sel_hi:[1,0]
	v_pk_mul_f32 v[106:107], v[106:107], v[230:231] op_sel_hi:[1,0]
	v_pk_mul_f32 v[104:105], v[104:105], v[230:231] op_sel_hi:[1,0]
	v_pk_mul_f32 v[102:103], v[102:103], v[230:231] op_sel_hi:[1,0]
	v_pk_mul_f32 v[100:101], v[100:101], v[230:231] op_sel_hi:[1,0]
	v_pk_mul_f32 v[120:121], v[98:99], v[230:231] op_sel_hi:[1,0]
	v_pk_mul_f32 v[112:113], v[96:97], v[230:231] op_sel_hi:[1,0]
	v_cvt_pk_bf16_f32 v96, v108, v109
	v_cvt_pk_bf16_f32 v97, v110, v111
	v_cvt_pk_bf16_f32 v98, v104, v105
	v_cvt_pk_bf16_f32 v99, v106, v107
	v_cvt_pk_bf16_f32 v100, v100, v101
	v_cvt_pk_bf16_f32 v101, v102, v103
	v_cvt_pk_bf16_f32 v102, v112, v113
	v_cvt_pk_bf16_f32 v103, v120, v121
	global_store_dwordx4 v[116:117], v[96:99], off
	global_store_dwordx4 v[116:117], v[100:103], off offset:256
	v_or_b32_e32 v98, 48, v148
	v_lshlrev_b64 v[100:101], 12, v[114:115]
	v_lshl_add_u64 v[100:101], s[6:7], 0, v[100:101]
	v_ashrrev_i32_e32 v99, 31, v98
	v_lshl_add_u64 v[100:101], v[100:101], 0, v[150:151]
	v_lshl_add_u64 v[102:103], v[98:99], 2, s[8:9]
	v_pk_mul_f32 v[94:95], v[94:95], v[232:233] op_sel_hi:[1,0]
	v_pk_mul_f32 v[92:93], v[92:93], v[232:233] op_sel_hi:[1,0]
	v_pk_mul_f32 v[90:91], v[90:91], v[232:233] op_sel_hi:[1,0]
	v_pk_mul_f32 v[88:89], v[88:89], v[232:233] op_sel_hi:[1,0]
	v_pk_mul_f32 v[86:87], v[86:87], v[232:233] op_sel_hi:[1,0]
	v_pk_mul_f32 v[84:85], v[84:85], v[232:233] op_sel_hi:[1,0]
	v_pk_mul_f32 v[104:105], v[82:83], v[232:233] op_sel_hi:[1,0]
	v_pk_mul_f32 v[96:97], v[80:81], v[232:233] op_sel_hi:[1,0]
	v_cvt_pk_bf16_f32 v80, v92, v93
	v_cvt_pk_bf16_f32 v81, v94, v95
	v_cvt_pk_bf16_f32 v82, v88, v89
	v_cvt_pk_bf16_f32 v83, v90, v91
	v_cvt_pk_bf16_f32 v84, v84, v85
	v_cvt_pk_bf16_f32 v85, v86, v87
	v_cvt_pk_bf16_f32 v86, v96, v97
; __device__ __forceinline__ unsigned pk2(float lo, float hi) { f32x2 v; v.x = lo; v.y = hi; return __builtin_bit_cast(unsigned, __builtin_convertvector(v, hwbf2)); }
; #define PG8_WAIT_V(n) asm volatile("s_waitcnt vmcnt(" #n ")" ::: "memory")
; #define PG8_BAR __builtin_amdgcn_s_barrier()
; template <class Epi>
; __device__ __forceinline__ void gemm_phase(LAS unsigned char* lds, const Gemm g, const StaticOrder& S, const Epi& E) {
;     ...
;     PG8_WAIT_V(0);
;     if (wr == 0) PG8_BAR;
;     PG8_BAR;
;     __device__ __forceinline__ void operator()(const f32x4 (&acc)[2][2][4][2], const pg8::Unit& u, int wr, int wc, int fr, int fq) const {
;         const int row0 = u.pm * 256 + wr * 64 + fr, col0 = u.pn * 256 + wc * 32 + 8 * fq;
; #pragma unroll
;         for (int ai = 0; ai < 2; ++ai)
; #pragma unroll
;             for (int m = 0; m < 4; ++m) { const int row = row0 + ai * 128 + m * 16; const float s = rstd[row]; bf16_t* rowp = O + (size_t)row * ldc + col0;
; #pragma unroll
;                 for (int bj = 0; bj < 2; ++bj) { const f32x4 v0 = acc[ai][bj][m][0] * s, v1 = acc[ai][bj][m][1] * s;
;                     u32x4 w; w.x = pk2(v0[0], v0[1]); w.y = pk2(v0[2], v0[3]); w.z = pk2(v1[0], v1[1]); w.w = pk2(v1[2], v1[3]);
;                     *(u32x4*)(rowp + bj * 128) = w; } }
	v_cvt_pk_bf16_f32 v87, v104, v105
	global_store_dwordx4 v[100:101], v[80:83], off
	global_store_dwordx4 v[100:101], v[84:87], off offset:256
	v_lshlrev_b64 v[82:83], 12, v[98:99]
	v_lshl_add_u64 v[82:83], s[6:7], 0, v[82:83]
	v_lshl_add_u64 v[82:83], v[82:83], 0, v[150:151]
	v_pk_mul_f32 v[78:79], v[78:79], v[234:235] op_sel_hi:[1,0]
	v_pk_mul_f32 v[76:77], v[76:77], v[234:235] op_sel_hi:[1,0]
	v_pk_mul_f32 v[74:75], v[74:75], v[234:235] op_sel_hi:[1,0]
	v_pk_mul_f32 v[72:73], v[72:73], v[234:235] op_sel_hi:[1,0]
	v_pk_mul_f32 v[70:71], v[70:71], v[234:235] op_sel_hi:[1,0]
	v_pk_mul_f32 v[68:69], v[68:69], v[234:235] op_sel_hi:[1,0]
	v_pk_mul_f32 v[84:85], v[66:67], v[234:235] op_sel_hi:[1,0]
	v_pk_mul_f32 v[80:81], v[64:65], v[234:235] op_sel_hi:[1,0]
	v_cvt_pk_bf16_f32 v64, v76, v77
	v_cvt_pk_bf16_f32 v65, v78, v79
	v_cvt_pk_bf16_f32 v66, v72, v73
	v_cvt_pk_bf16_f32 v67, v74, v75
	v_cvt_pk_bf16_f32 v68, v68, v69
	v_cvt_pk_bf16_f32 v69, v70, v71
	v_cvt_pk_bf16_f32 v70, v80, v81
	v_cvt_pk_bf16_f32 v71, v84, v85
	global_store_dwordx4 v[82:83], v[64:67], off
	global_store_dwordx4 v[82:83], v[68:71], off offset:256
	v_lshl_add_u64 v[66:67], v[146:147], 0, s[30:31]
	v_add_co_u32_e32 v68, vcc, s13, v146
	s_mov_b32 s13, 0x90000
	s_nop 0
	v_addc_co_u32_e32 v69, vcc, 0, v147, vcc
	s_mov_b64 s[30:31], 0x90000
	v_pk_mul_f32 v[62:63], v[62:63], v[236:237] op_sel_hi:[1,0]
	v_pk_mul_f32 v[60:61], v[60:61], v[236:237] op_sel_hi:[1,0]
	v_pk_mul_f32 v[58:59], v[58:59], v[236:237] op_sel_hi:[1,0]
	v_pk_mul_f32 v[56:57], v[56:57], v[236:237] op_sel_hi:[1,0]
	v_pk_mul_f32 v[54:55], v[54:55], v[236:237] op_sel_hi:[1,0]
	v_pk_mul_f32 v[52:53], v[52:53], v[236:237] op_sel_hi:[1,0]
	v_pk_mul_f32 v[70:71], v[50:51], v[236:237] op_sel_hi:[1,0]
	v_pk_mul_f32 v[64:65], v[48:49], v[236:237] op_sel_hi:[1,0]
	v_cvt_pk_bf16_f32 v48, v60, v61
	v_cvt_pk_bf16_f32 v49, v62, v63
	v_cvt_pk_bf16_f32 v50, v56, v57
	v_cvt_pk_bf16_f32 v51, v58, v59
	v_cvt_pk_bf16_f32 v52, v52, v53
	v_cvt_pk_bf16_f32 v53, v54, v55
	v_cvt_pk_bf16_f32 v54, v64, v65
	v_cvt_pk_bf16_f32 v55, v70, v71
	global_store_dwordx4 v[68:69], v[48:51], off
	global_store_dwordx4 v[66:67], v[52:55], off offset:256
	v_lshl_add_u64 v[50:51], v[146:147], 0, s[30:31]
	v_add_co_u32_e32 v52, vcc, s13, v146
	s_mov_b32 s13, 0xa0000
	s_nop 0
	v_addc_co_u32_e32 v53, vcc, 0, v147, vcc
	s_mov_b64 s[30:31], 0xa0000
	v_pk_mul_f32 v[46:47], v[46:47], v[238:239] op_sel_hi:[1,0]
	v_pk_mul_f32 v[44:45], v[44:45], v[238:239] op_sel_hi:[1,0]
	v_pk_mul_f32 v[42:43], v[42:43], v[238:239] op_sel_hi:[1,0]
	v_pk_mul_f32 v[40:41], v[40:41], v[238:239] op_sel_hi:[1,0]
	v_pk_mul_f32 v[38:39], v[38:39], v[238:239] op_sel_hi:[1,0]
	v_pk_mul_f32 v[36:37], v[36:37], v[238:239] op_sel_hi:[1,0]
	v_pk_mul_f32 v[54:55], v[34:35], v[238:239] op_sel_hi:[1,0]
	v_pk_mul_f32 v[48:49], v[32:33], v[238:239] op_sel_hi:[1,0]
	v_cvt_pk_bf16_f32 v32, v44, v45
	v_cvt_pk_bf16_f32 v33, v46, v47
	v_cvt_pk_bf16_f32 v34, v40, v41
	v_cvt_pk_bf16_f32 v35, v42, v43
	v_cvt_pk_bf16_f32 v36, v36, v37
	v_cvt_pk_bf16_f32 v37, v38, v39
	v_cvt_pk_bf16_f32 v38, v48, v49
	v_cvt_pk_bf16_f32 v39, v54, v55
	global_store_dwordx4 v[52:53], v[32:35], off
	global_store_dwordx4 v[50:51], v[36:39], off offset:256
	v_lshl_add_u64 v[34:35], v[146:147], 0, s[30:31]
	v_add_co_u32_e32 v36, vcc, s13, v146
	s_mov_b32 s13, 0xb0000
	s_nop 0
	v_addc_co_u32_e32 v37, vcc, 0, v147, vcc
	s_and_b64 vcc, exec, s[2:3]
	s_mov_b64 s[30:31], s[16:17]
	v_pk_mul_f32 v[30:31], v[30:31], v[240:241] op_sel_hi:[1,0]
	v_pk_mul_f32 v[28:29], v[28:29], v[240:241] op_sel_hi:[1,0]
	v_pk_mul_f32 v[26:27], v[26:27], v[240:241] op_sel_hi:[1,0]
	v_pk_mul_f32 v[24:25], v[24:25], v[240:241] op_sel_hi:[1,0]
	v_pk_mul_f32 v[22:23], v[22:23], v[240:241] op_sel_hi:[1,0]
	v_pk_mul_f32 v[20:21], v[20:21], v[240:241] op_sel_hi:[1,0]
	v_pk_mul_f32 v[38:39], v[18:19], v[240:241] op_sel_hi:[1,0]
	v_pk_mul_f32 v[32:33], v[16:17], v[240:241] op_sel_hi:[1,0]
	v_cvt_pk_bf16_f32 v16, v28, v29
	v_cvt_pk_bf16_f32 v17, v30, v31
	v_cvt_pk_bf16_f32 v18, v24, v25
	v_cvt_pk_bf16_f32 v19, v26, v27
	v_cvt_pk_bf16_f32 v20, v20, v21
	v_cvt_pk_bf16_f32 v21, v22, v23
	v_cvt_pk_bf16_f32 v22, v32, v33
	v_cvt_pk_bf16_f32 v23, v38, v39
	global_store_dwordx4 v[36:37], v[16:19], off
	global_store_dwordx4 v[34:35], v[20:23], off offset:256
	v_lshl_add_u64 v[18:19], v[146:147], 0, s[36:37]
	v_add_co_u32_e64 v20, s[2:3], s13, v146
	v_pk_mul_f32 v[14:15], v[14:15], v[242:243] op_sel_hi:[1,0]
	v_pk_mul_f32 v[12:13], v[12:13], v[242:243] op_sel_hi:[1,0]
	v_pk_mul_f32 v[10:11], v[10:11], v[242:243] op_sel_hi:[1,0]
	v_pk_mul_f32 v[8:9], v[8:9], v[242:243] op_sel_hi:[1,0]
	v_addc_co_u32_e64 v21, s[2:3], 0, v147, s[2:3]
	v_pk_mul_f32 v[6:7], v[6:7], v[242:243] op_sel_hi:[1,0]
	v_pk_mul_f32 v[4:5], v[4:5], v[242:243] op_sel_hi:[1,0]
	v_pk_mul_f32 v[22:23], v[2:3], v[242:243] op_sel_hi:[1,0]
	v_pk_mul_f32 v[16:17], v[0:1], v[242:243] op_sel_hi:[1,0]
	v_cvt_pk_bf16_f32 v0, v12, v13
	v_cvt_pk_bf16_f32 v1, v14, v15
	v_cvt_pk_bf16_f32 v2, v8, v9
	v_cvt_pk_bf16_f32 v3, v10, v11
	v_cvt_pk_bf16_f32 v4, v4, v5
	v_cvt_pk_bf16_f32 v5, v6, v7
	v_cvt_pk_bf16_f32 v6, v16, v17
	v_cvt_pk_bf16_f32 v7, v22, v23
	global_store_dwordx4 v[20:21], v[0:3], off
	global_store_dwordx4 v[18:19], v[4:7], off offset:256
	s_cbranch_vccz .LBB0_155
	s_waitcnt vmcnt(0)
	s_cmpk_gt_u32 s23, 0xff
	s_cbranch_scc1 .LBB0_166
	s_barrier

; #define PG8_STAGE(bufoff, gbase, voff) do { _Pragma("unroll") for (int _i = 0; _i < 2; ++_i) \
;         __builtin_amdgcn_global_load_lds((const unsigned*)((const char*)(gbase) + (voff)[_i]), (LAS unsigned*)(lds + (bufoff) + ldsw + _i * 8192), 16, 0, 0); } while (0)
; #define PG8_LDA(dst, b, h) do { _Pragma("unroll") for (int m = 0; m < 4; ++m) _Pragma("unroll") for (int k = 0; k < 2; ++k) dst[m][k] = *(const LAS bf16x8*)(lds + PG8_SA(b, h) + aoff + m * 2048 + k * 1024); } while (0)
; #define PG8_LDB(dst, b, h) do { _Pragma("unroll") for (int n = 0; n < 2; ++n) _Pragma("unroll") for (int k = 0; k < 2; ++k) dst[n][k] = *(const LAS bf16x8*)(lds + PG8_SB(b, h) + boff + n * 2048 + k * 1024); } while (0)
; #define PG8_SCHED __builtin_amdgcn_sched_barrier(0)
; template <class Epi>
; __device__ __forceinline__ void gemm_phase(LAS unsigned char* lds, const Gemm g, const StaticOrder& S, const Epi& E) {
;     ...
;         const bool has_next = S.next(ui + 1, nxt);
;         const char* nA = has_next ? (const char*)g.A + (size_t)nxt.pm * tstepA : cA; const char* nB = has_next ? (const char*)g.Bt + (size_t)nxt.pn * tstepB : cB;
;         for (int t = 0; t < nt; t += 2) {
;             const bool last = (t == nt - 2);
;             const char* a1 = cA + (size_t)(t + 1) * kstep;
;             const char* a2 = last ? nA : cA + (size_t)(t + 2) * kstep; const char* b2 = last ? nB : cB + (size_t)(t + 2) * kstep;
;             const char* a3 = a2 + kstep; const char* b3 = b2 + kstep;
;             PG8_LDB(B0, 0, 0); PG8_SCHED; PG8_LDA(At, 0, 0); PG8_STAGE(PG8_SA(1, 1), a1 + hstepA, voffA);
;     __device__ __forceinline__ void operator()(const f32x4 (&acc)[2][2][4][2], const pg8::Unit& u, int wr, int wc, int fr_, int fq_) const {
;     ...
;             for (int m = 0; m < 4; ++m) { const int row = 248 * u.pm + 62 * (2 * ai + wr) - 2 + 16 * m + fr; const int rc = row < 0 ? 0 : (row < R ? row : R - 1); const float sv = rstd3[rc]; sc[ai][m] = (row >= 0 && row < R) ? sv : 0.f; }
.LBB0_1131:
	s_ashr_i32 s31, s30, 31
	s_lshl_b64 s[36:37], s[30:31], 19
	s_add_u32 s36, s18, s36
	s_addc_u32 s37, s19, s37
	s_and_b64 s[2:3], s[2:3], exec
	s_cselect_b32 s5, s37, s41
	s_cselect_b32 s31, s36, s40
	s_add_u32 s45, s40, 0x100
	v_mov_b32_e32 v0, 0
	s_addc_u32 s46, s41, 0
	s_mov_b32 s47, -2
	v_mov_b32_e32 v1, v0
	v_mov_b32_e32 v2, v0
	v_mov_b32_e32 v3, v0
	v_mov_b32_e32 v32, v0
	v_mov_b32_e32 v33, v0
	v_mov_b32_e32 v34, v0
	v_mov_b32_e32 v35, v0
	v_mov_b32_e32 v4, v0
	v_mov_b32_e32 v5, v0
	v_mov_b32_e32 v6, v0
	v_mov_b32_e32 v7, v0
	v_mov_b32_e32 v36, v0
	v_mov_b32_e32 v37, v0
	v_mov_b32_e32 v38, v0
	v_mov_b32_e32 v39, v0
	v_mov_b32_e32 v8, v0
	v_mov_b32_e32 v9, v0
	v_mov_b32_e32 v10, v0
	v_mov_b32_e32 v11, v0
	v_mov_b32_e32 v40, v0
	v_mov_b32_e32 v41, v0
	v_mov_b32_e32 v42, v0
	v_mov_b32_e32 v43, v0
	v_mov_b32_e32 v12, v0
	v_mov_b32_e32 v13, v0
	v_mov_b32_e32 v14, v0
	v_mov_b32_e32 v15, v0
	v_mov_b32_e32 v44, v0
	v_mov_b32_e32 v45, v0
	v_mov_b32_e32 v46, v0
	v_mov_b32_e32 v47, v0
	v_mov_b32_e32 v16, v0
	v_mov_b32_e32 v17, v0
	v_mov_b32_e32 v18, v0
	v_mov_b32_e32 v19, v0
	v_mov_b32_e32 v48, v0
	v_mov_b32_e32 v49, v0
	v_mov_b32_e32 v50, v0
	v_mov_b32_e32 v51, v0
	v_mov_b32_e32 v20, v0
	v_mov_b32_e32 v21, v0
	v_mov_b32_e32 v22, v0
	v_mov_b32_e32 v23, v0
	v_mov_b32_e32 v52, v0
	v_mov_b32_e32 v53, v0
	v_mov_b32_e32 v54, v0
	v_mov_b32_e32 v55, v0
	v_mov_b32_e32 v24, v0
	v_mov_b32_e32 v25, v0
	v_mov_b32_e32 v26, v0
	v_mov_b32_e32 v27, v0
	v_mov_b32_e32 v56, v0
	v_mov_b32_e32 v57, v0
	v_mov_b32_e32 v58, v0
	v_mov_b32_e32 v59, v0
	v_mov_b32_e32 v28, v0
	v_mov_b32_e32 v29, v0
	v_mov_b32_e32 v30, v0
	v_mov_b32_e32 v31, v0
	v_mov_b32_e32 v60, v0
	v_mov_b32_e32 v61, v0
	v_mov_b32_e32 v62, v0
	v_mov_b32_e32 v63, v0
	v_mov_b32_e32 v64, v0
	v_mov_b32_e32 v65, v0
	v_mov_b32_e32 v66, v0
	v_mov_b32_e32 v67, v0
	v_mov_b32_e32 v112, v0
	v_mov_b32_e32 v113, v0
	v_mov_b32_e32 v114, v0
	v_mov_b32_e32 v115, v0
	v_mov_b32_e32 v68, v0
	v_mov_b32_e32 v69, v0
	v_mov_b32_e32 v70, v0
	v_mov_b32_e32 v71, v0
	v_mov_b32_e32 v116, v0
	v_mov_b32_e32 v117, v0
	v_mov_b32_e32 v118, v0
	v_mov_b32_e32 v119, v0
	v_mov_b32_e32 v72, v0
	v_mov_b32_e32 v73, v0
	v_mov_b32_e32 v74, v0
	v_mov_b32_e32 v75, v0
	v_mov_b32_e32 v120, v0
	v_mov_b32_e32 v121, v0
	v_mov_b32_e32 v122, v0
	v_mov_b32_e32 v123, v0
	v_mov_b32_e32 v76, v0
	v_mov_b32_e32 v77, v0
	v_mov_b32_e32 v78, v0
	v_mov_b32_e32 v79, v0
	v_mov_b32_e32 v124, v0
	v_mov_b32_e32 v125, v0
	v_mov_b32_e32 v126, v0
	v_mov_b32_e32 v127, v0
	v_mov_b32_e32 v80, v0
	v_mov_b32_e32 v81, v0
	v_mov_b32_e32 v82, v0
	v_mov_b32_e32 v83, v0
	v_mov_b32_e32 v128, v0
	v_mov_b32_e32 v129, v0
	v_mov_b32_e32 v130, v0
	v_mov_b32_e32 v131, v0
	v_mov_b32_e32 v84, v0
	v_mov_b32_e32 v85, v0
	v_mov_b32_e32 v86, v0
	v_mov_b32_e32 v87, v0
	v_mov_b32_e32 v132, v0
	v_mov_b32_e32 v133, v0
	v_mov_b32_e32 v134, v0
	v_mov_b32_e32 v135, v0
	v_mov_b32_e32 v88, v0
	v_mov_b32_e32 v89, v0
	v_mov_b32_e32 v90, v0
	v_mov_b32_e32 v91, v0
	v_mov_b32_e32 v136, v0
	v_mov_b32_e32 v137, v0
	v_mov_b32_e32 v138, v0
	v_mov_b32_e32 v139, v0
	v_mov_b32_e32 v92, v0
	v_mov_b32_e32 v93, v0
	v_mov_b32_e32 v94, v0
	v_mov_b32_e32 v95, v0
	v_mov_b32_e32 v140, v0
	v_mov_b32_e32 v141, v0
	v_mov_b32_e32 v142, v0
	v_mov_b32_e32 v143, v0
	s_mul_i32 s64, s44, 0xf8
	s_add_i32 s64, s64, -2
	v_add_u32_e32 v230, s64, v215
	v_add_u32_e32 v231, s57, v230
	v_add_u32_e32 v232, 16, v231
	v_add_u32_e32 v233, 32, v231
	v_add_u32_e32 v234, 48, v231
	v_add_u32_e32 v235, s58, v230
	v_add_u32_e32 v236, 16, v235
	v_add_u32_e32 v237, 32, v235
	v_add_u32_e32 v238, 48, v235
	v_med3_i32 v231, v231, 0, v222
	v_med3_i32 v232, v232, 0, v222
	v_med3_i32 v233, v233, 0, v222
	v_med3_i32 v234, v234, 0, v222
	v_med3_i32 v235, v235, 0, v222
	v_med3_i32 v236, v236, 0, v222
	v_med3_i32 v237, v237, 0, v222
	v_med3_i32 v238, v238, 0, v222
	v_lshlrev_b32_e32 v231, 2, v231
	v_lshlrev_b32_e32 v232, 2, v232
	v_lshlrev_b32_e32 v233, 2, v233
	v_lshlrev_b32_e32 v234, 2, v234
	v_lshlrev_b32_e32 v235, 2, v235
	v_lshlrev_b32_e32 v236, 2, v236
	v_lshlrev_b32_e32 v237, 2, v237
	v_lshlrev_b32_e32 v238, 2, v238
	global_load_dword v245, v231, s[10:11]
	global_load_dword v246, v232, s[10:11]
	global_load_dword v247, v233, s[10:11]
	global_load_dword v248, v234, s[10:11]
	global_load_dword v249, v235, s[10:11]
	global_load_dword v250, v236, s[10:11]
	global_load_dword v251, v237, s[10:11]
	global_load_dword v252, v238, s[10:11]
; #define PG8_STAGE(bufoff, gbase, voff) do { _Pragma("unroll") for (int _i = 0; _i < 2; ++_i) \
;         __builtin_amdgcn_global_load_lds((const unsigned*)((const char*)(gbase) + (voff)[_i]), (LAS unsigned*)(lds + (bufoff) + ldsw + _i * 8192), 16, 0, 0); } while (0)
; #define PG8_LDA(dst, b, h) do { _Pragma("unroll") for (int m = 0; m < 4; ++m) _Pragma("unroll") for (int k = 0; k < 2; ++k) dst[m][k] = *(const LAS bf16x8*)(lds + PG8_SA(b, h) + aoff + m * 2048 + k * 1024); } while (0)
; #define PG8_LDB(dst, b, h) do { _Pragma("unroll") for (int n = 0; n < 2; ++n) _Pragma("unroll") for (int k = 0; k < 2; ++k) dst[n][k] = *(const LAS bf16x8*)(lds + PG8_SB(b, h) + boff + n * 2048 + k * 1024); } while (0)
; #define PG8_MMA(ai, bj, At, Bt) do { __builtin_amdgcn_s_setprio(1); _Pragma("unroll") for (int m = 0; m < 4; ++m) _Pragma("unroll") for (int n = 0; n < 2; ++n) _Pragma("unroll") for (int k = 0; k < 2; ++k) \
;         acc[ai][bj][m][n] = __builtin_amdgcn_mfma_f32_16x16x32_bf16(Bt[n][k], At[m][k], acc[ai][bj][m][n], 0, 0, 0); __builtin_amdgcn_s_setprio(0); } while (0)
; #define PG8_WAIT_L(n) asm volatile("s_waitcnt lgkmcnt(" #n ")" ::: "memory")
; #define PG8_BAR __builtin_amdgcn_s_barrier()
; #define PG8_SCHED __builtin_amdgcn_sched_barrier(0)
; template <class Epi>
; __device__ __forceinline__ void gemm_phase(LAS unsigned char* lds, const Gemm g, const StaticOrder& S, const Epi& E) {
;     ...
;             PG8_LDB(B0, 0, 0); PG8_SCHED; PG8_LDA(At, 0, 0); PG8_STAGE(PG8_SA(1, 1), a1 + hstepA, voffA);
;             PG8_WAIT_L(8); PG8_BAR; PG8_WAIT_L(0); PG8_MMA(0, 0, At, B0); PG8_BAR; PG8_SCHED;
;             PG8_LDB(B1, 0, 1); PG8_STAGE(PG8_SB(0, 0), b2, voffB);
;             PG8_BAR; PG8_WAIT_L(0); PG8_MMA(0, 1, At, B1); PG8_BAR;
;             PG8_LDA(At, 0, 1); PG8_STAGE(PG8_SA(0, 0), a2, voffA);
;             PG8_BAR; PG8_WAIT_L(0); PG8_MMA(1, 0, At, B0); PG8_BAR; PG8_SCHED;
.LBB0_1132:
	ds_read_b128 v[96:99], v218
	ds_read_b128 v[100:103], v218 offset:1024
	ds_read_b128 v[104:107], v218 offset:2048
	ds_read_b128 v[108:111], v218 offset:3072
	s_add_u32 s2, s38, 0x100
	s_addc_u32 s3, s39, 0
	s_cmp_eq_u32 s47, 12
	s_cselect_b32 s43, s35, s3
	s_cselect_b32 s42, s34, s2
	s_cselect_b32 s41, s5, s46
	s_cselect_b32 s40, s31, s45
	v_lshl_add_u64 v[194:195], s[38:39], 0, v[186:187]
	s_add_i32 m0, s48, 0xc000
	ds_read_b128 v[144:147], v219
	ds_read_b128 v[148:151], v219 offset:1024
	ds_read_b128 v[152:155], v219 offset:2048
	ds_read_b128 v[156:159], v219 offset:3072
	ds_read_b128 v[160:163], v219 offset:4096
	ds_read_b128 v[164:167], v219 offset:5120
	ds_read_b128 v[168:171], v219 offset:6144
	ds_read_b128 v[172:175], v219 offset:7168
	global_load_lds_dwordx4 v[194:195], off
	v_lshl_add_u64 v[194:195], s[38:39], 0, v[188:189]
	s_add_i32 m0, s48, 0xe000
	s_nop 0
	global_load_lds_dwordx4 v[194:195], off
	s_waitcnt lgkmcnt(8)
	s_barrier
	s_waitcnt lgkmcnt(0)
	s_setprio 1
	s_waitcnt lgkmcnt(0)
	v_mfma_f32_16x16x32_bf16 v[140:143], v[96:99], v[144:147], v[140:143]
	v_mfma_f32_16x16x32_bf16 v[92:95], v[104:107], v[144:147], v[92:95]
	v_mfma_f32_16x16x32_bf16 v[136:139], v[96:99], v[152:155], v[136:139]
	v_mfma_f32_16x16x32_bf16 v[88:91], v[104:107], v[152:155], v[88:91]
	v_mfma_f32_16x16x32_bf16 v[132:135], v[96:99], v[160:163], v[132:135]
	v_mfma_f32_16x16x32_bf16 v[84:87], v[104:107], v[160:163], v[84:87]
	v_mfma_f32_16x16x32_bf16 v[128:131], v[96:99], v[168:171], v[128:131]
	v_mfma_f32_16x16x32_bf16 v[80:83], v[104:107], v[168:171], v[80:83]
	v_mfma_f32_16x16x32_bf16 v[140:143], v[100:103], v[148:151], v[140:143]
	v_mfma_f32_16x16x32_bf16 v[92:95], v[108:111], v[148:151], v[92:95]
	v_mfma_f32_16x16x32_bf16 v[136:139], v[100:103], v[156:159], v[136:139]
	v_mfma_f32_16x16x32_bf16 v[88:91], v[108:111], v[156:159], v[88:91]
	v_mfma_f32_16x16x32_bf16 v[132:135], v[100:103], v[164:167], v[132:135]
	v_mfma_f32_16x16x32_bf16 v[84:87], v[108:111], v[164:167], v[84:87]
	v_mfma_f32_16x16x32_bf16 v[128:131], v[100:103], v[172:175], v[128:131]
	v_mfma_f32_16x16x32_bf16 v[80:83], v[108:111], v[172:175], v[80:83]
	s_setprio 0
	s_barrier
	s_add_i32 s38, s63, s33
	v_lshl_add_u64 v[210:211], s[40:41], 0, v[180:181]
	s_mov_b32 m0, s38
	ds_read_b128 v[194:197], v220
	ds_read_b128 v[198:201], v220 offset:1024
	ds_read_b128 v[202:205], v220 offset:2048
	ds_read_b128 v[206:209], v220 offset:3072
	global_load_lds_dwordx4 v[210:211], off
	v_lshl_add_u64 v[224:225], s[40:41], 0, v[184:185]
	s_add_i32 m0, s38, 0x2000
	s_nop 0
	global_load_lds_dwordx4 v[224:225], off
	s_barrier
	s_waitcnt lgkmcnt(0)
	s_setprio 1
	s_waitcnt lgkmcnt(0)
	v_mfma_f32_16x16x32_bf16 v[124:127], v[194:197], v[144:147], v[124:127]
	v_mfma_f32_16x16x32_bf16 v[76:79], v[202:205], v[144:147], v[76:79]
	v_mfma_f32_16x16x32_bf16 v[120:123], v[194:197], v[152:155], v[120:123]
	v_mfma_f32_16x16x32_bf16 v[72:75], v[202:205], v[152:155], v[72:75]
	v_mfma_f32_16x16x32_bf16 v[116:119], v[194:197], v[160:163], v[116:119]
	v_mfma_f32_16x16x32_bf16 v[68:71], v[202:205], v[160:163], v[68:71]
	v_mfma_f32_16x16x32_bf16 v[112:115], v[194:197], v[168:171], v[112:115]
	v_mfma_f32_16x16x32_bf16 v[64:67], v[202:205], v[168:171], v[64:67]
	v_mfma_f32_16x16x32_bf16 v[124:127], v[198:201], v[148:151], v[124:127]
	v_mfma_f32_16x16x32_bf16 v[76:79], v[206:209], v[148:151], v[76:79]
	v_mfma_f32_16x16x32_bf16 v[120:123], v[198:201], v[156:159], v[120:123]
	v_mfma_f32_16x16x32_bf16 v[72:75], v[206:209], v[156:159], v[72:75]
	v_mfma_f32_16x16x32_bf16 v[116:119], v[198:201], v[164:167], v[116:119]
	v_mfma_f32_16x16x32_bf16 v[68:71], v[206:209], v[164:167], v[68:71]
	v_mfma_f32_16x16x32_bf16 v[112:115], v[198:201], v[172:175], v[112:115]
	v_mfma_f32_16x16x32_bf16 v[64:67], v[206:209], v[172:175], v[64:67]
	s_setprio 0
	s_mov_b32 m0, s48
	v_lshl_add_u64 v[226:227], s[42:43], 0, v[178:179]
	s_barrier
	ds_read_b128 v[144:147], v219 offset:16384
	ds_read_b128 v[148:151], v219 offset:17408
	ds_read_b128 v[152:155], v219 offset:18432
	ds_read_b128 v[156:159], v219 offset:19456
	ds_read_b128 v[160:163], v219 offset:20480
	ds_read_b128 v[164:167], v219 offset:21504
	ds_read_b128 v[168:171], v219 offset:22528
	ds_read_b128 v[172:175], v219 offset:23552
	global_load_lds_dwordx4 v[226:227], off
	v_lshl_add_u64 v[228:229], s[42:43], 0, v[182:183]
	s_mov_b32 m0, s49
	s_nop 0
	global_load_lds_dwordx4 v[228:229], off
	s_barrier
	s_waitcnt lgkmcnt(0)
	s_setprio 1
	s_waitcnt lgkmcnt(0)
	v_mfma_f32_16x16x32_bf16 v[60:63], v[96:99], v[144:147], v[60:63]
	v_mfma_f32_16x16x32_bf16 v[28:31], v[104:107], v[144:147], v[28:31]
	v_mfma_f32_16x16x32_bf16 v[56:59], v[96:99], v[152:155], v[56:59]
	v_mfma_f32_16x16x32_bf16 v[24:27], v[104:107], v[152:155], v[24:27]
	v_mfma_f32_16x16x32_bf16 v[52:55], v[96:99], v[160:163], v[52:55]
	v_mfma_f32_16x16x32_bf16 v[20:23], v[104:107], v[160:163], v[20:23]
	v_mfma_f32_16x16x32_bf16 v[48:51], v[96:99], v[168:171], v[48:51]
	v_mfma_f32_16x16x32_bf16 v[16:19], v[104:107], v[168:171], v[16:19]
	v_mfma_f32_16x16x32_bf16 v[60:63], v[100:103], v[148:151], v[60:63]
	v_mfma_f32_16x16x32_bf16 v[28:31], v[108:111], v[148:151], v[28:31]
	v_mfma_f32_16x16x32_bf16 v[56:59], v[100:103], v[156:159], v[56:59]
	v_mfma_f32_16x16x32_bf16 v[24:27], v[108:111], v[156:159], v[24:27]
	v_mfma_f32_16x16x32_bf16 v[52:55], v[100:103], v[164:167], v[52:55]
	v_mfma_f32_16x16x32_bf16 v[20:23], v[108:111], v[164:167], v[20:23]
	v_mfma_f32_16x16x32_bf16 v[48:51], v[100:103], v[172:175], v[48:51]
	v_mfma_f32_16x16x32_bf16 v[16:19], v[108:111], v[172:175], v[16:19]
	s_setprio 0
	s_barrier
; #define PG8_STAGE(bufoff, gbase, voff) do { _Pragma("unroll") for (int _i = 0; _i < 2; ++_i) \
;         __builtin_amdgcn_global_load_lds((const unsigned*)((const char*)(gbase) + (voff)[_i]), (LAS unsigned*)(lds + (bufoff) + ldsw + _i * 8192), 16, 0, 0); } while (0)
; #define PG8_LDA(dst, b, h) do { _Pragma("unroll") for (int m = 0; m < 4; ++m) _Pragma("unroll") for (int k = 0; k < 2; ++k) dst[m][k] = *(const LAS bf16x8*)(lds + PG8_SA(b, h) + aoff + m * 2048 + k * 1024); } while (0)
; #define PG8_LDB(dst, b, h) do { _Pragma("unroll") for (int n = 0; n < 2; ++n) _Pragma("unroll") for (int k = 0; k < 2; ++k) dst[n][k] = *(const LAS bf16x8*)(lds + PG8_SB(b, h) + boff + n * 2048 + k * 1024); } while (0)
; #define PG8_MMA(ai, bj, At, Bt) do { __builtin_amdgcn_s_setprio(1); _Pragma("unroll") for (int m = 0; m < 4; ++m) _Pragma("unroll") for (int n = 0; n < 2; ++n) _Pragma("unroll") for (int k = 0; k < 2; ++k) \
;         acc[ai][bj][m][n] = __builtin_amdgcn_mfma_f32_16x16x32_bf16(Bt[n][k], At[m][k], acc[ai][bj][m][n], 0, 0, 0); __builtin_amdgcn_s_setprio(0); } while (0)
; #define PG8_WAIT_V(n) asm volatile("s_waitcnt vmcnt(" #n ")" ::: "memory")
; #define PG8_WAIT_L(n) asm volatile("s_waitcnt lgkmcnt(" #n ")" ::: "memory")
; #define PG8_BAR __builtin_amdgcn_s_barrier()
; #define PG8_SCHED __builtin_amdgcn_sched_barrier(0)
; template <class Epi>
; __device__ __forceinline__ void gemm_phase(LAS unsigned char* lds, const Gemm g, const StaticOrder& S, const Epi& E) {
;     ...
;             PG8_STAGE(PG8_SB(0, 1), b2 + hstepB, voffB);
;             PG8_WAIT_V(6); PG8_BAR; PG8_MMA(1, 1, At, B1); PG8_BAR;
;             PG8_LDB(B0, 1, 0); PG8_SCHED; PG8_LDA(At, 1, 0); PG8_STAGE(PG8_SA(0, 1), a2 + hstepA, voffA);
;             PG8_WAIT_L(8); PG8_BAR; PG8_WAIT_L(0); PG8_MMA(0, 0, At, B0); PG8_BAR; PG8_SCHED;
;             PG8_LDB(B1, 1, 1); PG8_STAGE(PG8_SB(1, 0), b3, voffB);
;             PG8_BAR; PG8_WAIT_L(0); PG8_MMA(0, 1, At, B1); PG8_BAR;
;             PG8_LDA(At, 1, 1); PG8_STAGE(PG8_SA(1, 0), a3, voffA);
	s_add_u32 s38, s40, 0x40000
	s_addc_u32 s39, s41, 0
	s_add_i32 s71, s22, s33
	v_lshl_add_u64 v[96:97], s[38:39], 0, v[180:181]
	s_mov_b32 m0, s71
	s_nop 0
	global_load_lds_dwordx4 v[96:97], off
	v_lshl_add_u64 v[96:97], s[38:39], 0, v[184:185]
	s_add_i32 m0, s71, 0x2000
	s_nop 0
	global_load_lds_dwordx4 v[96:97], off
	s_waitcnt vmcnt(6)
	s_barrier
	s_setprio 1
	v_mfma_f32_16x16x32_bf16 v[44:47], v[194:197], v[144:147], v[44:47]
	v_mfma_f32_16x16x32_bf16 v[12:15], v[202:205], v[144:147], v[12:15]
	v_mfma_f32_16x16x32_bf16 v[40:43], v[194:197], v[152:155], v[40:43]
	v_mfma_f32_16x16x32_bf16 v[8:11], v[202:205], v[152:155], v[8:11]
	v_mfma_f32_16x16x32_bf16 v[36:39], v[194:197], v[160:163], v[36:39]
	v_mfma_f32_16x16x32_bf16 v[4:7], v[202:205], v[160:163], v[4:7]
	v_mfma_f32_16x16x32_bf16 v[32:35], v[194:197], v[168:171], v[32:35]
	v_mfma_f32_16x16x32_bf16 v[0:3], v[202:205], v[168:171], v[0:3]
	v_mfma_f32_16x16x32_bf16 v[44:47], v[198:201], v[148:151], v[44:47]
	v_mfma_f32_16x16x32_bf16 v[12:15], v[206:209], v[148:151], v[12:15]
	v_mfma_f32_16x16x32_bf16 v[40:43], v[198:201], v[156:159], v[40:43]
	v_mfma_f32_16x16x32_bf16 v[8:11], v[206:209], v[156:159], v[8:11]
	v_mfma_f32_16x16x32_bf16 v[36:39], v[198:201], v[164:167], v[36:39]
	v_mfma_f32_16x16x32_bf16 v[4:7], v[206:209], v[164:167], v[4:7]
	v_mfma_f32_16x16x32_bf16 v[32:35], v[198:201], v[172:175], v[32:35]
	v_mfma_f32_16x16x32_bf16 v[0:3], v[206:209], v[172:175], v[0:3]
	s_setprio 0
	s_add_i32 s71, 0, 0x18000
	v_add_u32_e32 v108, s71, v217
	s_barrier
	ds_read_b128 v[96:99], v108
	ds_read_b128 v[100:103], v108 offset:1024
	ds_read_b128 v[104:107], v108 offset:2048
	ds_read_b128 v[108:111], v108 offset:3072
	s_add_u32 s38, s42, 0x3e000
	s_addc_u32 s39, s43, 0
	s_mov_b32 m0, s50
	v_lshl_add_u64 v[194:195], s[38:39], 0, v[178:179]
	ds_read_b128 v[144:147], v219 offset:32768
	ds_read_b128 v[148:151], v219 offset:33792
	ds_read_b128 v[152:155], v219 offset:34816
	ds_read_b128 v[156:159], v219 offset:35840
	ds_read_b128 v[160:163], v219 offset:36864
	ds_read_b128 v[164:167], v219 offset:37888
	ds_read_b128 v[168:171], v219 offset:38912
	ds_read_b128 v[172:175], v219 offset:39936
	global_load_lds_dwordx4 v[194:195], off
	v_lshl_add_u64 v[194:195], s[38:39], 0, v[182:183]
	s_mov_b32 m0, s51
	s_nop 0
	global_load_lds_dwordx4 v[194:195], off
	s_waitcnt lgkmcnt(8)
	s_barrier
	s_waitcnt lgkmcnt(0)
	s_setprio 1
	s_waitcnt lgkmcnt(0)
	v_mfma_f32_16x16x32_bf16 v[140:143], v[96:99], v[144:147], v[140:143]
	v_mfma_f32_16x16x32_bf16 v[92:95], v[104:107], v[144:147], v[92:95]
	v_mfma_f32_16x16x32_bf16 v[136:139], v[96:99], v[152:155], v[136:139]
	v_mfma_f32_16x16x32_bf16 v[88:91], v[104:107], v[152:155], v[88:91]
	v_mfma_f32_16x16x32_bf16 v[132:135], v[96:99], v[160:163], v[132:135]
	v_mfma_f32_16x16x32_bf16 v[84:87], v[104:107], v[160:163], v[84:87]
	v_mfma_f32_16x16x32_bf16 v[128:131], v[96:99], v[168:171], v[128:131]
	v_mfma_f32_16x16x32_bf16 v[80:83], v[104:107], v[168:171], v[80:83]
	v_mfma_f32_16x16x32_bf16 v[140:143], v[100:103], v[148:151], v[140:143]
	v_mfma_f32_16x16x32_bf16 v[92:95], v[108:111], v[148:151], v[92:95]
	v_mfma_f32_16x16x32_bf16 v[136:139], v[100:103], v[156:159], v[136:139]
	v_mfma_f32_16x16x32_bf16 v[88:91], v[108:111], v[156:159], v[88:91]
	v_mfma_f32_16x16x32_bf16 v[132:135], v[100:103], v[164:167], v[132:135]
	v_mfma_f32_16x16x32_bf16 v[84:87], v[108:111], v[164:167], v[84:87]
	v_mfma_f32_16x16x32_bf16 v[128:131], v[100:103], v[172:175], v[128:131]
	v_mfma_f32_16x16x32_bf16 v[80:83], v[108:111], v[172:175], v[80:83]
	s_setprio 0
	s_barrier
	s_add_i32 s42, 0, 0x1c000
	s_add_i32 s38, s71, s33
	v_add_u32_e32 v206, s42, v217
	v_lshl_add_u64 v[210:211], v[210:211], 0, s[12:13]
	s_mov_b32 m0, s38
	ds_read_b128 v[194:197], v206
	ds_read_b128 v[198:201], v206 offset:1024
	ds_read_b128 v[202:205], v206 offset:2048
	ds_read_b128 v[206:209], v206 offset:3072
	global_load_lds_dwordx4 v[210:211], off
	v_lshl_add_u64 v[210:211], v[224:225], 0, s[12:13]
	s_add_i32 m0, s38, 0x2000
	s_nop 0
	global_load_lds_dwordx4 v[210:211], off
	s_barrier
	s_waitcnt lgkmcnt(0)
	s_setprio 1
	s_waitcnt lgkmcnt(0)
	v_mfma_f32_16x16x32_bf16 v[124:127], v[194:197], v[144:147], v[124:127]
	v_mfma_f32_16x16x32_bf16 v[76:79], v[202:205], v[144:147], v[76:79]
	v_mfma_f32_16x16x32_bf16 v[120:123], v[194:197], v[152:155], v[120:123]
	v_mfma_f32_16x16x32_bf16 v[72:75], v[202:205], v[152:155], v[72:75]
	v_mfma_f32_16x16x32_bf16 v[116:119], v[194:197], v[160:163], v[116:119]
	v_mfma_f32_16x16x32_bf16 v[68:71], v[202:205], v[160:163], v[68:71]
	v_mfma_f32_16x16x32_bf16 v[112:115], v[194:197], v[168:171], v[112:115]
	v_mfma_f32_16x16x32_bf16 v[64:67], v[202:205], v[168:171], v[64:67]
	v_mfma_f32_16x16x32_bf16 v[124:127], v[198:201], v[148:151], v[124:127]
	v_mfma_f32_16x16x32_bf16 v[76:79], v[206:209], v[148:151], v[76:79]
	v_mfma_f32_16x16x32_bf16 v[120:123], v[198:201], v[156:159], v[120:123]
	v_mfma_f32_16x16x32_bf16 v[72:75], v[206:209], v[156:159], v[72:75]
	v_mfma_f32_16x16x32_bf16 v[116:119], v[198:201], v[164:167], v[116:119]
	v_mfma_f32_16x16x32_bf16 v[68:71], v[206:209], v[164:167], v[68:71]
	v_mfma_f32_16x16x32_bf16 v[112:115], v[198:201], v[172:175], v[112:115]
	v_mfma_f32_16x16x32_bf16 v[64:67], v[206:209], v[172:175], v[64:67]
	s_setprio 0
	s_mov_b32 m0, s55
	v_lshl_add_u64 v[210:211], v[226:227], 0, s[12:13]
	s_barrier
	ds_read_b128 v[144:147], v219 offset:49152
	ds_read_b128 v[148:151], v219 offset:50176
	ds_read_b128 v[152:155], v219 offset:51200
	ds_read_b128 v[156:159], v219 offset:52224
	ds_read_b128 v[160:163], v219 offset:53248
	ds_read_b128 v[164:167], v219 offset:54272
	ds_read_b128 v[168:171], v219 offset:55296
	ds_read_b128 v[172:175], v219 offset:56320
	global_load_lds_dwordx4 v[210:211], off
	v_lshl_add_u64 v[210:211], v[228:229], 0, s[12:13]
	s_mov_b32 m0, s56
	s_nop 0
	global_load_lds_dwordx4 v[210:211], off
	s_barrier
; #define PG8_STAGE(bufoff, gbase, voff) do { _Pragma("unroll") for (int _i = 0; _i < 2; ++_i) \
;         __builtin_amdgcn_global_load_lds((const unsigned*)((const char*)(gbase) + (voff)[_i]), (LAS unsigned*)(lds + (bufoff) + ldsw + _i * 8192), 16, 0, 0); } while (0)
; #define PG8_MMA(ai, bj, At, Bt) do { __builtin_amdgcn_s_setprio(1); _Pragma("unroll") for (int m = 0; m < 4; ++m) _Pragma("unroll") for (int n = 0; n < 2; ++n) _Pragma("unroll") for (int k = 0; k < 2; ++k) \
;         acc[ai][bj][m][n] = __builtin_amdgcn_mfma_f32_16x16x32_bf16(Bt[n][k], At[m][k], acc[ai][bj][m][n], 0, 0, 0); __builtin_amdgcn_s_setprio(0); } while (0)
; #define PG8_WAIT_V(n) asm volatile("s_waitcnt vmcnt(" #n ")" ::: "memory")
; #define PG8_WAIT_L(n) asm volatile("s_waitcnt lgkmcnt(" #n ")" ::: "memory")
; #define PG8_BAR __builtin_amdgcn_s_barrier()
; template <class Epi>
; __device__ __forceinline__ void gemm_phase(LAS unsigned char* lds, const Gemm g, const StaticOrder& S, const Epi& E) {
;     ...
;             PG8_BAR; PG8_WAIT_L(0); PG8_MMA(1, 0, At, B0); PG8_BAR; PG8_SCHED;
;             PG8_STAGE(PG8_SB(1, 1), b3 + hstepB, voffB);
;             PG8_WAIT_V(6); PG8_BAR; PG8_MMA(1, 1, At, B1); PG8_BAR;
;     __device__ __forceinline__ void operator()(const f32x4 (&acc)[2][2][4][2], const pg8::Unit& u, int wr, int wc, int fr_, int fq_) const {
;     ...
;             for (int m = 0; m < 4; ++m) { const int row = 248 * u.pm + 62 * (2 * ai + wr) - 2 + 16 * m + fr; const int rc = row < 0 ? 0 : (row < R ? row : R - 1); const float sv = rstd3[rc]; sc[ai][m] = (row >= 0 && row < R) ? sv : 0.f; }
;         f32x4 wn[4];
;         { const int colb = j0; wn[0] = *(const f32x4*)(cw + colb); wn[1] = *(const f32x4*)(cw + NUP + colb); wn[2] = *(const f32x4*)(cw + 2 * NUP + colb); wn[3] = *(const f32x4*)(cb + colb); }
;         float cgv[4][4];
; #pragma unroll
;         for (int sp = 0; sp < 8; ++sp) {
;             const int ai = sp >> 2, n = (sp >> 1) & 1, bj = sp & 1;
;             const int rowbase = 248 * u.pm + 62 * (2 * ai + wr) - 2;
;             const f32x4 w0 = wn[0], w1 = wn[1], w2 = wn[2], bb = wn[3];
;             if (sp < 7) { const int sq = sp + 1, n2 = (sq >> 1) & 1, bj2 = sq & 1, colb = bj2 * DFF + j0 + 4 * n2;
;                 wn[0] = *(const f32x4*)(cw + colb); wn[1] = *(const f32x4*)(cw + NUP + colb); wn[2] = *(const f32x4*)(cw + 2 * NUP + colb); wn[3] = *(const f32x4*)(cb + colb); }
	s_waitcnt lgkmcnt(0)
	s_setprio 1
	s_waitcnt lgkmcnt(0)
	v_mfma_f32_16x16x32_bf16 v[60:63], v[96:99], v[144:147], v[60:63]
	v_mfma_f32_16x16x32_bf16 v[28:31], v[104:107], v[144:147], v[28:31]
	v_mfma_f32_16x16x32_bf16 v[56:59], v[96:99], v[152:155], v[56:59]
	v_mfma_f32_16x16x32_bf16 v[24:27], v[104:107], v[152:155], v[24:27]
	v_mfma_f32_16x16x32_bf16 v[52:55], v[96:99], v[160:163], v[52:55]
	v_mfma_f32_16x16x32_bf16 v[20:23], v[104:107], v[160:163], v[20:23]
	v_mfma_f32_16x16x32_bf16 v[48:51], v[96:99], v[168:171], v[48:51]
	v_mfma_f32_16x16x32_bf16 v[16:19], v[104:107], v[168:171], v[16:19]
	v_mfma_f32_16x16x32_bf16 v[60:63], v[100:103], v[148:151], v[60:63]
	v_mfma_f32_16x16x32_bf16 v[28:31], v[108:111], v[148:151], v[28:31]
	v_mfma_f32_16x16x32_bf16 v[56:59], v[100:103], v[156:159], v[56:59]
	v_mfma_f32_16x16x32_bf16 v[24:27], v[108:111], v[156:159], v[24:27]
	v_mfma_f32_16x16x32_bf16 v[52:55], v[100:103], v[164:167], v[52:55]
	v_mfma_f32_16x16x32_bf16 v[20:23], v[108:111], v[164:167], v[20:23]
	v_mfma_f32_16x16x32_bf16 v[48:51], v[100:103], v[172:175], v[48:51]
	v_mfma_f32_16x16x32_bf16 v[16:19], v[108:111], v[172:175], v[16:19]
	s_setprio 0
	s_barrier
	s_add_u32 s38, s40, 0x40080
	s_addc_u32 s39, s41, 0
	s_add_i32 s40, s42, s33
	v_lshl_add_u64 v[96:97], s[38:39], 0, v[180:181]
	s_mov_b32 m0, s40
	s_nop 0
	global_load_lds_dwordx4 v[96:97], off
	v_lshl_add_u64 v[96:97], s[38:39], 0, v[184:185]
	s_add_i32 m0, s40, 0x2000
	s_nop 0
	global_load_lds_dwordx4 v[96:97], off
	s_waitcnt vmcnt(6)
	s_barrier
	s_setprio 1
	v_mfma_f32_16x16x32_bf16 v[44:47], v[194:197], v[144:147], v[44:47]
	v_mfma_f32_16x16x32_bf16 v[12:15], v[202:205], v[144:147], v[12:15]
	v_mfma_f32_16x16x32_bf16 v[40:43], v[194:197], v[152:155], v[40:43]
	v_mfma_f32_16x16x32_bf16 v[8:11], v[202:205], v[152:155], v[8:11]
	v_mfma_f32_16x16x32_bf16 v[36:39], v[194:197], v[160:163], v[36:39]
	v_mfma_f32_16x16x32_bf16 v[4:7], v[202:205], v[160:163], v[4:7]
	v_mfma_f32_16x16x32_bf16 v[32:35], v[194:197], v[168:171], v[32:35]
	v_mfma_f32_16x16x32_bf16 v[0:3], v[202:205], v[168:171], v[0:3]
	v_mfma_f32_16x16x32_bf16 v[44:47], v[198:201], v[148:151], v[44:47]
	v_mfma_f32_16x16x32_bf16 v[12:15], v[206:209], v[148:151], v[12:15]
	v_mfma_f32_16x16x32_bf16 v[40:43], v[198:201], v[156:159], v[40:43]
	v_mfma_f32_16x16x32_bf16 v[8:11], v[206:209], v[156:159], v[8:11]
	v_mfma_f32_16x16x32_bf16 v[36:39], v[198:201], v[164:167], v[36:39]
	v_mfma_f32_16x16x32_bf16 v[4:7], v[206:209], v[164:167], v[4:7]
	v_mfma_f32_16x16x32_bf16 v[32:35], v[198:201], v[172:175], v[32:35]
	v_mfma_f32_16x16x32_bf16 v[0:3], v[206:209], v[172:175], v[0:3]
	s_setprio 0
	s_add_i32 s47, s47, 2
	s_add_u32 s45, s45, 0x100
	s_addc_u32 s46, s46, 0
	s_cmp_gt_u32 s47, 13
	s_mov_b64 s[38:39], s[2:3]
	s_barrier
	s_cbranch_scc0 .LBB0_1132
	s_mul_i32 s31, s44, 0xf8
	v_mov_b32_e32 v207, v215
	v_mov_b32_e32 v96, v216
	s_add_i32 s31, s31, -2
	s_lshl_b32 s2, s4, 7
	v_add_u32_e32 v97, s31, v207
	v_add_u32_e32 v168, s57, v97
	v_med3_i32 v98, v168, 0, v222
	v_add_u32_e32 v169, 16, v168
	v_add_u32_e32 v170, 32, v168
	v_lshlrev_b32_e32 v98, 2, v98
	v_med3_i32 v99, v169, 0, v222
	v_med3_i32 v100, v170, 0, v222
	v_add_u32_e32 v209, 48, v168
	v_lshlrev_b32_e32 v99, 2, v99
	v_lshlrev_b32_e32 v100, 2, v100
	v_mov_b32_e32 v171, v245
	v_mov_b32_e32 v204, v246
	v_mov_b32_e32 v206, v247
	v_med3_i32 v98, v209, 0, v222
	v_lshlrev_b32_e32 v98, 2, v98
	v_mov_b32_e32 v211, v248
	v_lshl_add_u32 v205, v96, 4, v207
	v_lshlrev_b32_e32 v98, 3, v207
	s_or_b32 s2, s2, s54
	v_and_b32_e32 v225, 24, v98
	v_add_u32_e32 v237, s58, v97
	v_and_b32_e32 v230, -4, v205
	v_lshl_add_u32 v224, v96, 3, s62
	v_med3_i32 v96, v237, 0, v222
	v_add_u32_e32 v233, 16, v237
	v_add_u32_e32 v232, 32, v237
	v_or_b32_e32 v194, s2, v225
	v_mul_lo_u32 v229, v230, 40
	v_lshlrev_b32_e32 v98, 2, v96
	v_med3_i32 v96, v233, 0, v222
	v_med3_i32 v97, v232, 0, v222
	v_ashrrev_i32_e32 v195, 31, v194
	v_subrev_u32_e32 v100, 40, v229
	v_cmp_lt_i32_e64 s[2:3], 3, v205
	v_readlane_b32 s64, v254, 23
	v_lshlrev_b32_e32 v102, 2, v96
	v_lshlrev_b32_e32 v103, 2, v97
	v_lshlrev_b64 v[96:97], 2, v[194:195]
	v_cndmask_b32_e64 v100, 0, v100, s[2:3]
	v_readlane_b32 s74, v254, 33
	v_readlane_b32 s75, v254, 34
	v_add_u32_e32 v144, s62, v100
	v_add_u32_e32 v226, v144, v225
	v_lshl_add_u64 v[196:197], s[74:75], 0, v[96:97]
	v_add_co_u32_e32 v144, vcc, s52, v196
	v_lshl_add_u64 v[198:199], s[14:15], 0, v[96:97]
	s_nop 0
	v_addc_co_u32_e32 v145, vcc, 0, v197, vcc
	v_add_co_u32_e32 v146, vcc, s52, v198
	v_add_u32_e32 v231, 48, v237
	s_nop 0
	v_addc_co_u32_e32 v147, vcc, 0, v199, vcc
	v_med3_i32 v99, v231, 0, v222
	v_cmp_gt_u32_e32 vcc, s81, v168
	v_add_u32_e32 v101, 0xffffffb0, v229
	v_lshlrev_b32_e32 v99, 2, v99
	v_readlane_b32 s76, v254, 35
	v_readlane_b32 s77, v254, 36
	v_cndmask_b32_e64 v228, 0, v101, s[2:3]
	v_mov_b32_e32 v238, v249
	v_mov_b32_e32 v236, v250
	v_mov_b32_e32 v235, v251
	v_mov_b32_e32 v234, v252
	v_lshl_add_u64 v[200:201], s[16:17], 0, v[96:97]
	v_lshl_add_u64 v[202:203], s[76:77], 0, v[96:97]
	global_load_dwordx4 v[104:107], v[196:197], off offset:16
	global_load_dwordx4 v[164:167], v[196:197], off
	global_load_dwordx4 v[100:103], v[198:199], off offset:16
	global_load_dwordx4 v[160:163], v[198:199], off
	global_load_dwordx4 v[96:99], v[200:201], off offset:16
	global_load_dwordx4 v[156:159], v[200:201], off
	global_load_dwordx4 v[108:111], v[202:203], off offset:16
	global_load_dwordx4 v[172:175], v[202:203], off
	global_load_dwordx4 v[148:151], v[144:145], off offset:3072
	global_load_dwordx4 v[152:155], v[146:147], off offset:3072
	s_add_i32 s46, s31, s57
	v_add_u32_e32 v241, s46, v230
; #define LAS __attribute__((address_space(3)))
; __device__ __forceinline__ float bf2f(unsigned v) { return __uint_as_float(v << 16); }
; __device__ __forceinline__ unsigned pk2(float lo, float hi) { f32x2 v; v.x = lo; v.y = hi; return __builtin_bit_cast(unsigned, __builtin_convertvector(v, hwbf2)); }
;     __device__ __forceinline__ void operator()(const f32x4 (&acc)[2][2][4][2], const pg8::Unit& u, int wr, int wc, int fr_, int fq_) const {
;     ...
;             for (int m = 0; m < 4; ++m) { const f32x4 v = acc[ai][bj][m][n] * sc[ai][m];
;                 u32x2 w; w.x = pk2(v[0], v[1]); w.y = pk2(v[2], v[3]); *(LAS u32x2*)(slab + (16 * m + fr) * SLAB_LD + fq * 8) = w; }
;             f32x4 p2, p1;
;             { const int h1 = rs > 0 ? 4 * rs - 1 : 0, h2 = rs > 0 ? 4 * rs - 2 : 0;
;                 const u32x2 q1 = *(const LAS u32x2*)(slab + h1 * SLAB_LD + cq * 8), q2 = *(const LAS u32x2*)(slab + h2 * SLAB_LD + cq * 8);
;                 p1[0] = bf2f(q1.x & 0xffff); p1[1] = bf2f(q1.x >> 16); p1[2] = bf2f(q1.y & 0xffff); p1[3] = bf2f(q1.y >> 16);
;                 p2[0] = bf2f(q2.x & 0xffff); p2[1] = bf2f(q2.x >> 16); p2[2] = bf2f(q2.y & 0xffff); p2[3] = bf2f(q2.y >> 16); }
; #pragma unroll
;             for (int i = 0; i < 4; ++i) {
;                 const int lr = 4 * rs + i, row = rowbase + lr;
;                 const u32x2 q0 = *(const LAS u32x2*)(slab + lr * SLAB_LD + cq * 8);
;                 f32x4 cur; cur[0] = bf2f(q0.x & 0xffff); cur[1] = bf2f(q0.x >> 16); cur[2] = bf2f(q0.y & 0xffff); cur[3] = bf2f(q0.y >> 16);
;                 const bool smp = row >= RP;
;                 const int t = smp ? ((row - RP) & (DSEQ - 1)) : (row & (SEQ - 1));
;                 const bool valid = (lr >= 2) && (row < R) && (t >= 2);
;                 const f32x4 cv = bb + w0 * p2 + w1 * p1 + w2 * cur;
;                 p2 = p1; p1 = cur;
;                 if (bj == 0) { cgv[i][0] = cv[0]; cgv[i][1] = cv[1]; cgv[i][2] = cv[2]; cgv[i][3] = cv[3]; }
;                 else { u32x2 w; w.x = pk2(gelu_tanh(cgv[i][0]) * cv[0], gelu_tanh(cgv[i][1]) * cv[1]); w.y = pk2(gelu_tanh(cgv[i][2]) * cv[2], gelu_tanh(cgv[i][3]) * cv[3]); if (valid) *(u32x2*)(act + (size_t)row * DFF + j0 + 4 * n) = w; }
	v_readlane_b32 s65, v254, 24
	v_readlane_b32 s66, v254, 25
	v_readlane_b32 s67, v254, 26
	v_readlane_b32 s68, v254, 27
	v_readlane_b32 s69, v254, 28
	v_readlane_b32 s70, v254, 29
	v_readlane_b32 s71, v254, 30
	v_readlane_b32 s72, v254, 31
	v_readlane_b32 s73, v254, 32
	v_readlane_b32 s78, v254, 37
	v_readlane_b32 s79, v254, 38
	v_cndmask_b32_e32 v210, 0, v171, vcc
	v_cmp_gt_u32_e32 vcc, s81, v169
	v_pk_mul_f32 v[142:143], v[142:143], v[210:211] op_sel_hi:[1,0]
	s_nop 0
	v_cndmask_b32_e32 v208, 0, v204, vcc
	v_cmp_gt_u32_e32 vcc, s81, v170
	v_pk_mul_f32 v[140:141], v[140:141], v[210:211] op_sel_hi:[1,0]
	v_pk_mul_f32 v[138:139], v[138:139], v[208:209] op_sel_hi:[1,0]
	v_cndmask_b32_e32 v206, 0, v206, vcc
	v_cmp_gt_u32_e32 vcc, s81, v209
	v_cvt_pk_bf16_f32 v140, v140, v141
	v_cvt_pk_bf16_f32 v141, v142, v143
	v_cndmask_b32_e32 v204, 0, v211, vcc
	v_add_co_u32_e32 v144, vcc, s52, v200
	v_mul_lo_u32 v142, v207, 40
	s_nop 0
	v_addc_co_u32_e32 v145, vcc, 0, v201, vcc
	v_add_co_u32_e32 v168, vcc, s52, v202
	global_load_dwordx4 v[144:147], v[144:145], off offset:3072
	s_nop 0
	v_addc_co_u32_e32 v169, vcc, 0, v203, vcc
	global_load_dwordx4 v[168:171], v[168:169], off offset:3072
	v_pk_mul_f32 v[136:137], v[136:137], v[208:209] op_sel_hi:[1,0]
	v_pk_mul_f32 v[134:135], v[134:135], v[206:207] op_sel_hi:[1,0]
	v_pk_mul_f32 v[132:133], v[132:133], v[206:207] op_sel_hi:[1,0]
	v_pk_mul_f32 v[130:131], v[130:131], v[204:205] op_sel_hi:[1,0]
	v_pk_mul_f32 v[128:129], v[128:129], v[204:205] op_sel_hi:[1,0]
	v_add_u32_e32 v227, v224, v142
	v_cvt_pk_bf16_f32 v136, v136, v137
	v_cvt_pk_bf16_f32 v137, v138, v139
	v_cvt_pk_bf16_f32 v132, v132, v133
	v_cvt_pk_bf16_f32 v133, v134, v135
	v_cvt_pk_bf16_f32 v128, v128, v129
	v_cvt_pk_bf16_f32 v129, v130, v131
	ds_write_b64 v227, v[140:141]
	ds_write_b64 v227, v[136:137] offset:640
	ds_write_b64 v227, v[132:133] offset:1280
	ds_write_b64 v227, v[128:129] offset:1920
	ds_read_b64 v[128:129], v226
	v_add_u32_e32 v130, s62, v228
	v_add_u32_e32 v132, s62, v225
	v_add_u32_e32 v228, v130, v225
	v_add_u32_e32 v225, v132, v229
	v_or_b32_e32 v229, 3, v205
	v_mul_lo_u32 v133, v229, 40
	v_pk_mul_f32 v[126:127], v[126:127], v[210:211] op_sel_hi:[1,0]
	v_pk_mul_f32 v[124:125], v[124:125], v[210:211] op_sel_hi:[1,0]
	v_pk_mul_f32 v[122:123], v[122:123], v[208:209] op_sel_hi:[1,0]
	v_pk_mul_f32 v[120:121], v[120:121], v[208:209] op_sel_hi:[1,0]
	v_pk_mul_f32 v[118:119], v[118:119], v[206:207] op_sel_hi:[1,0]
	v_pk_mul_f32 v[116:117], v[116:117], v[206:207] op_sel_hi:[1,0]
	v_pk_mul_f32 v[114:115], v[114:115], v[204:205] op_sel_hi:[1,0]
	v_pk_mul_f32 v[112:113], v[112:113], v[204:205] op_sel_hi:[1,0]
	v_add_u32_e32 v224, v132, v133
	v_cvt_pk_bf16_f32 v124, v124, v125
	v_cvt_pk_bf16_f32 v125, v126, v127
	v_cvt_pk_bf16_f32 v120, v120, v121
	v_cvt_pk_bf16_f32 v121, v122, v123
	v_cvt_pk_bf16_f32 v116, v116, v117
	v_cvt_pk_bf16_f32 v117, v118, v119
	v_cvt_pk_bf16_f32 v112, v112, v113
	v_cvt_pk_bf16_f32 v113, v114, v115
	ds_read_b64 v[142:143], v228
	s_waitcnt lgkmcnt(0)
	v_lshlrev_b32_e32 v136, 16, v128
	v_and_b32_e32 v137, 0xffff0000, v128
	v_lshlrev_b32_e32 v138, 16, v129
	v_and_b32_e32 v139, 0xffff0000, v129
	ds_read_b64 v[140:141], v225
	ds_read2_b64 v[128:131], v225 offset0:5 offset1:10
	ds_read_b64 v[132:133], v224
	ds_write_b64 v227, v[124:125]
	ds_write_b64 v227, v[120:121] offset:640
	ds_write_b64 v227, v[116:117] offset:1280
	ds_write_b64 v227, v[112:113] offset:1920
	ds_read_b64 v[112:113], v226
	ds_read_b64 v[114:115], v225
	v_cmp_gt_i32_e32 vcc, s81, v241
	s_and_b64 s[4:5], s[2:3], vcc
	v_cmp_lt_i32_e32 vcc, s82, v241
	s_waitcnt lgkmcnt(8)
	v_lshlrev_b32_e32 v134, 16, v140
	v_and_b32_e32 v135, 0xffff0000, v140
	v_cndmask_b32_e64 v118, v223, 30, vcc
	v_and_b32_e32 v118, v118, v241
	v_cmp_ne_u32_e32 vcc, 0, v118
	v_lshlrev_b32_e32 v116, 16, v141
	v_and_b32_e32 v117, 0xffff0000, v141
	s_waitcnt lgkmcnt(1)
	v_lshlrev_b32_e32 v126, 16, v112
	v_and_b32_e32 v127, 0xffff0000, v112
	v_lshlrev_b32_e32 v140, 16, v113
	v_and_b32_e32 v141, 0xffff0000, v113
	s_waitcnt lgkmcnt(0)
	v_lshlrev_b32_e32 v112, 16, v114
	v_and_b32_e32 v113, 0xffff0000, v114
	v_lshlrev_b32_e32 v114, 16, v115
	v_and_b32_e32 v115, 0xffff0000, v115
	s_and_b64 s[38:39], s[4:5], vcc
	s_waitcnt vmcnt(0)
	s_and_saveexec_b64 s[4:5], s[38:39]
	s_cbranch_execz .LBB0_1135
	v_lshlrev_b32_e32 v122, 16, v142
	v_and_b32_e32 v123, 0xffff0000, v142
	v_lshlrev_b32_e32 v124, 16, v143
	v_and_b32_e32 v125, 0xffff0000, v143
	v_pk_fma_f32 v[122:123], v[164:165], v[122:123], v[172:173]
	v_pk_fma_f32 v[124:125], v[166:167], v[124:125], v[174:175]
	v_pk_fma_f32 v[122:123], v[160:161], v[136:137], v[122:123]
	v_pk_fma_f32 v[124:125], v[162:163], v[138:139], v[124:125]
	v_pk_fma_f32 v[122:123], v[156:157], v[134:135], v[122:123]
	v_pk_fma_f32 v[124:125], v[158:159], v[116:117], v[124:125]
	v_mul_f32_e32 v207, v122, v122
	v_mul_f32_e32 v142, v124, v124
	v_mul_f32_e32 v143, v125, v125
	v_fmamk_f32 v207, v207, 0xbdd2d3e2, v221
	v_mul_f32_e32 v209, v123, v123
	v_fmamk_f32 v142, v142, 0xbdd2d3e2, v221
	v_fmamk_f32 v143, v143, 0xbdd2d3e2, v221
	v_mul_f32_e32 v207, v122, v207
	v_fmamk_f32 v209, v209, 0xbdd2d3e2, v221
	v_mul_f32_e32 v142, v124, v142
	v_mul_f32_e32 v143, v125, v143
	v_exp_f32_e32 v207, v207
	v_mul_f32_e32 v209, v123, v209
	v_exp_f32_e32 v142, v142
	v_exp_f32_e32 v143, v143
	v_exp_f32_e32 v209, v209
	ds_read_b64 v[118:119], v228
	v_add_f32_e32 v207, 1.0, v207
	v_add_f32_e32 v142, 1.0, v142
	v_add_f32_e32 v143, 1.0, v143
	v_rcp_f32_e32 v242, v207
	v_add_f32_e32 v207, 1.0, v209
	v_rcp_f32_e32 v142, v142
	v_rcp_f32_e32 v143, v143
	v_rcp_f32_e32 v243, v207
	s_waitcnt lgkmcnt(0)
	v_lshlrev_b32_e32 v120, 16, v118
	v_and_b32_e32 v121, 0xffff0000, v118
	v_lshlrev_b32_e32 v118, 16, v119
	v_and_b32_e32 v119, 0xffff0000, v119
	v_pk_fma_f32 v[120:121], v[148:149], v[120:121], v[168:169]
	v_pk_fma_f32 v[118:119], v[150:151], v[118:119], v[170:171]
	v_pk_fma_f32 v[120:121], v[152:153], v[126:127], v[120:121]
	v_pk_fma_f32 v[118:119], v[154:155], v[140:141], v[118:119]
	v_pk_fma_f32 v[120:121], v[144:145], v[112:113], v[120:121]
	v_pk_fma_f32 v[118:119], v[146:147], v[114:115], v[118:119]
	v_pk_mul_f32 v[124:125], v[124:125], v[142:143]
	v_pk_mul_f32 v[122:123], v[122:123], v[242:243]
	v_pk_mul_f32 v[118:119], v[124:125], v[118:119]
	v_pk_mul_f32 v[120:121], v[122:123], v[120:121]
	v_cvt_pk_bf16_f32 v119, v118, v119
	v_cvt_pk_bf16_f32 v118, v120, v121
	v_mov_b64_e32 v[120:121], s[8:9]
	v_mad_i64_i32 v[120:121], s[40:41], v241, s83, v[120:121]
	v_lshl_add_u64 v[120:121], v[194:195], 1, v[120:121]
	global_store_dwordx2 v[120:121], v[118:119], off
